# phase 7: MFMA-block priority 3 for workgroups bid<256 and 1 for their CU partners (asymmetric, to de-phase the two workgroups of a CU)
# baseline (speedup 1.0000x reference)
.Lgu2_pair:
	s_barrier
	s_cmpk_lt_u32 s60, 0x100
	s_cselect_b64 vcc, -1, 0
	s_mov_b32 s52, 0
.Lgu2_loop:
	v_add_u32_e32 v234, s22, v232
	v_add_u32_e32 v236, s28, v232
	v_add_u32_e32 v235, s22, v233
	v_add_u32_e32 v237, s28, v233
	ds_read_b128 v[136:139], v234
	ds_read_b128 v[140:143], v234 offset:2048
	ds_read_b128 v[144:147], v234 offset:4096
	ds_read_b128 v[148:151], v234 offset:6144
	ds_read_b128 v[188:191], v236
	ds_read_b128 v[196:199], v236 offset:2048
	ds_read_b128 v[200:203], v236 offset:4096
	ds_read_b128 v[204:207], v236 offset:6144
	ds_read_b128 v[172:175], v235
	ds_read_b128 v[176:179], v235 offset:2048
	ds_read_b128 v[180:183], v235 offset:4096
	ds_read_b128 v[184:187], v235 offset:6144
	ds_read_b128 v[212:215], v237
	ds_read_b128 v[216:219], v237 offset:2048
	ds_read_b128 v[220:223], v237 offset:4096
	ds_read_b128 v[224:227], v237 offset:6144
	s_add_i32 m0, s51, 0xc000
	s_nop 0
	global_load_lds_dwordx4 v228, s[44:45]
	s_add_i32 m0, s51, 0xc400
	s_nop 0
	global_load_lds_dwordx4 v230, s[44:45]
	s_add_i32 m0, s51, 0xe000
	s_nop 0
	global_load_lds_dwordx4 v229, s[44:45]
	s_add_i32 m0, s51, 0xe400
	s_nop 0
	global_load_lds_dwordx4 v231, s[44:45]
	s_add_i32 m0, s51, 0x10000
	s_nop 0
	global_load_lds_dwordx4 v228, s[46:47]
	s_add_i32 m0, s51, 0x10400
	s_nop 0
	global_load_lds_dwordx4 v230, s[46:47]
	s_waitcnt lgkmcnt(8)
	s_setprio 1
	s_cbranch_vccz .Lgu2_ap1
	s_setprio 3
.Lgu2_ap1:
	v_mfma_f32_16x16x32_bf16 v[2:5], v[136:139], v[188:191], v[2:5]
	v_mfma_f32_16x16x32_bf16 v[6:9], v[136:139], v[196:199], v[6:9]
	v_mfma_f32_16x16x32_bf16 v[10:13], v[136:139], v[200:203], v[10:13]
	v_mfma_f32_16x16x32_bf16 v[14:17], v[136:139], v[204:207], v[14:17]
	v_mfma_f32_16x16x32_bf16 v[18:21], v[140:143], v[188:191], v[18:21]
	v_mfma_f32_16x16x32_bf16 v[22:25], v[140:143], v[196:199], v[22:25]
	v_mfma_f32_16x16x32_bf16 v[26:29], v[140:143], v[200:203], v[26:29]
	v_mfma_f32_16x16x32_bf16 v[30:33], v[140:143], v[204:207], v[30:33]
	v_mfma_f32_16x16x32_bf16 v[34:37], v[144:147], v[188:191], v[34:37]
	v_mfma_f32_16x16x32_bf16 v[38:41], v[144:147], v[196:199], v[38:41]
	v_mfma_f32_16x16x32_bf16 v[42:45], v[144:147], v[200:203], v[42:45]
	v_mfma_f32_16x16x32_bf16 v[46:49], v[144:147], v[204:207], v[46:49]
	v_mfma_f32_16x16x32_bf16 v[50:53], v[148:151], v[188:191], v[50:53]
	v_mfma_f32_16x16x32_bf16 v[54:57], v[148:151], v[196:199], v[54:57]
	v_mfma_f32_16x16x32_bf16 v[58:61], v[148:151], v[200:203], v[58:61]
	v_mfma_f32_16x16x32_bf16 v[62:65], v[148:151], v[204:207], v[62:65]
	s_waitcnt lgkmcnt(0)
	v_mfma_f32_16x16x32_bf16 v[2:5], v[172:175], v[212:215], v[2:5]
	v_mfma_f32_16x16x32_bf16 v[6:9], v[172:175], v[216:219], v[6:9]
	v_mfma_f32_16x16x32_bf16 v[10:13], v[172:175], v[220:223], v[10:13]
	v_mfma_f32_16x16x32_bf16 v[14:17], v[172:175], v[224:227], v[14:17]
	v_mfma_f32_16x16x32_bf16 v[18:21], v[176:179], v[212:215], v[18:21]
	v_mfma_f32_16x16x32_bf16 v[22:25], v[176:179], v[216:219], v[22:25]
	v_mfma_f32_16x16x32_bf16 v[26:29], v[176:179], v[220:223], v[26:29]
	v_mfma_f32_16x16x32_bf16 v[30:33], v[176:179], v[224:227], v[30:33]
	v_mfma_f32_16x16x32_bf16 v[34:37], v[180:183], v[212:215], v[34:37]
	v_mfma_f32_16x16x32_bf16 v[38:41], v[180:183], v[216:219], v[38:41]
	v_mfma_f32_16x16x32_bf16 v[42:45], v[180:183], v[220:223], v[42:45]
	v_mfma_f32_16x16x32_bf16 v[46:49], v[180:183], v[224:227], v[46:49]
	v_mfma_f32_16x16x32_bf16 v[50:53], v[184:187], v[212:215], v[50:53]
	v_mfma_f32_16x16x32_bf16 v[54:57], v[184:187], v[216:219], v[54:57]
	v_mfma_f32_16x16x32_bf16 v[58:61], v[184:187], v[220:223], v[58:61]
	v_mfma_f32_16x16x32_bf16 v[62:65], v[184:187], v[224:227], v[62:65]
	s_setprio 0
	s_waitcnt vmcnt(6)
	s_barrier
.Lgu2_loop_a0:
	v_add_u32_e32 v236, s40, v232
	v_add_u32_e32 v237, s40, v233
	ds_read_b128 v[188:191], v236
	ds_read_b128 v[196:199], v236 offset:2048
	ds_read_b128 v[200:203], v236 offset:4096
	ds_read_b128 v[204:207], v236 offset:6144
	ds_read_b128 v[212:215], v237
	ds_read_b128 v[216:219], v237 offset:2048
	ds_read_b128 v[220:223], v237 offset:4096
	ds_read_b128 v[224:227], v237 offset:6144
	s_mov_b32 m0, s51
	s_nop 0
	global_load_lds_dwordx4 v229, s[46:47]
	s_add_i32 m0, s51, 0x400
	s_nop 0
	global_load_lds_dwordx4 v231, s[46:47]
	s_add_i32 m0, s51, 0x2000
	s_nop 0
	global_load_lds_dwordx4 v228, s[48:49]
	s_add_i32 m0, s51, 0x2400
	s_nop 0
	global_load_lds_dwordx4 v230, s[48:49]
	s_add_i32 m0, s51, 0x4000
	s_nop 0
	global_load_lds_dwordx4 v229, s[48:49]
	s_add_i32 m0, s51, 0x4400
	s_nop 0
	global_load_lds_dwordx4 v231, s[48:49]
	s_waitcnt lgkmcnt(4)
	s_setprio 1
	s_cbranch_vccz .Lgu2_ap2
	s_setprio 3
.Lgu2_ap2:
	v_mfma_f32_16x16x32_bf16 v[66:69], v[136:139], v[188:191], v[66:69]
	v_mfma_f32_16x16x32_bf16 v[70:73], v[136:139], v[196:199], v[70:73]
	v_mfma_f32_16x16x32_bf16 v[74:77], v[136:139], v[200:203], v[74:77]
	v_mfma_f32_16x16x32_bf16 v[78:81], v[136:139], v[204:207], v[78:81]
	v_mfma_f32_16x16x32_bf16 v[82:85], v[140:143], v[188:191], v[82:85]
	v_mfma_f32_16x16x32_bf16 v[86:89], v[140:143], v[196:199], v[86:89]
	v_mfma_f32_16x16x32_bf16 v[90:93], v[140:143], v[200:203], v[90:93]
	v_mfma_f32_16x16x32_bf16 v[94:97], v[140:143], v[204:207], v[94:97]
	v_mfma_f32_16x16x32_bf16 v[98:101], v[144:147], v[188:191], v[98:101]
	v_mfma_f32_16x16x32_bf16 v[102:105], v[144:147], v[196:199], v[102:105]
	v_mfma_f32_16x16x32_bf16 v[106:109], v[144:147], v[200:203], v[106:109]
	v_mfma_f32_16x16x32_bf16 v[110:113], v[144:147], v[204:207], v[110:113]
	v_mfma_f32_16x16x32_bf16 v[114:117], v[148:151], v[188:191], v[114:117]
	v_mfma_f32_16x16x32_bf16 v[118:121], v[148:151], v[196:199], v[118:121]
	v_mfma_f32_16x16x32_bf16 v[122:125], v[148:151], v[200:203], v[122:125]
	v_mfma_f32_16x16x32_bf16 v[126:129], v[148:151], v[204:207], v[126:129]
	s_waitcnt lgkmcnt(0)
	v_mfma_f32_16x16x32_bf16 v[66:69], v[172:175], v[212:215], v[66:69]
	v_mfma_f32_16x16x32_bf16 v[70:73], v[172:175], v[216:219], v[70:73]
	v_mfma_f32_16x16x32_bf16 v[74:77], v[172:175], v[220:223], v[74:77]
	v_mfma_f32_16x16x32_bf16 v[78:81], v[172:175], v[224:227], v[78:81]
	v_mfma_f32_16x16x32_bf16 v[82:85], v[176:179], v[212:215], v[82:85]
	v_mfma_f32_16x16x32_bf16 v[86:89], v[176:179], v[216:219], v[86:89]
	v_mfma_f32_16x16x32_bf16 v[90:93], v[176:179], v[220:223], v[90:93]
	v_mfma_f32_16x16x32_bf16 v[94:97], v[176:179], v[224:227], v[94:97]
	v_mfma_f32_16x16x32_bf16 v[98:101], v[180:183], v[212:215], v[98:101]
	v_mfma_f32_16x16x32_bf16 v[102:105], v[180:183], v[216:219], v[102:105]
	v_mfma_f32_16x16x32_bf16 v[106:109], v[180:183], v[220:223], v[106:109]
	v_mfma_f32_16x16x32_bf16 v[110:113], v[180:183], v[224:227], v[110:113]
	v_mfma_f32_16x16x32_bf16 v[114:117], v[184:187], v[212:215], v[114:117]
	v_mfma_f32_16x16x32_bf16 v[118:121], v[184:187], v[216:219], v[118:121]
	v_mfma_f32_16x16x32_bf16 v[122:125], v[184:187], v[220:223], v[122:125]
	v_mfma_f32_16x16x32_bf16 v[126:129], v[184:187], v[224:227], v[126:129]
	s_setprio 0
	v_add_u32_e32 v228, 0x80, v228
	v_add_u32_e32 v229, 0x80, v229
	v_add_u32_e32 v230, 0x80, v230
	v_add_u32_e32 v231, 0x80, v231
	s_waitcnt vmcnt(4)
	s_barrier
	v_add_u32_e32 v234, s23, v232
	v_add_u32_e32 v236, s29, v232
	v_add_u32_e32 v235, s23, v233
	v_add_u32_e32 v237, s29, v233
	ds_read_b128 v[136:139], v234
	ds_read_b128 v[140:143], v234 offset:2048
	ds_read_b128 v[144:147], v234 offset:4096
	ds_read_b128 v[148:151], v234 offset:6144
	ds_read_b128 v[188:191], v236
	ds_read_b128 v[196:199], v236 offset:2048
	ds_read_b128 v[200:203], v236 offset:4096
	ds_read_b128 v[204:207], v236 offset:6144
	ds_read_b128 v[172:175], v235
	ds_read_b128 v[176:179], v235 offset:2048
	ds_read_b128 v[180:183], v235 offset:4096
	ds_read_b128 v[184:187], v235 offset:6144
	ds_read_b128 v[212:215], v237
	ds_read_b128 v[216:219], v237 offset:2048
	ds_read_b128 v[220:223], v237 offset:4096
	ds_read_b128 v[224:227], v237 offset:6144
	s_add_i32 m0, s51, 0x6000
	s_nop 0
	global_load_lds_dwordx4 v228, s[44:45]
	s_add_i32 m0, s51, 0x6400
	s_nop 0
	global_load_lds_dwordx4 v230, s[44:45]
	s_add_i32 m0, s51, 0x8000
	s_nop 0
	global_load_lds_dwordx4 v229, s[44:45]
	s_add_i32 m0, s51, 0x8400
	s_nop 0
	global_load_lds_dwordx4 v231, s[44:45]
	s_add_i32 m0, s51, 0xa000
	s_nop 0
	global_load_lds_dwordx4 v228, s[46:47]
	s_add_i32 m0, s51, 0xa400
	s_nop 0
	global_load_lds_dwordx4 v230, s[46:47]
	s_waitcnt lgkmcnt(8)
	s_setprio 1
	s_cbranch_vccz .Lgu2_ap3
	s_setprio 3
.Lgu2_ap3:
	v_mfma_f32_16x16x32_bf16 v[2:5], v[136:139], v[188:191], v[2:5]
	v_mfma_f32_16x16x32_bf16 v[6:9], v[136:139], v[196:199], v[6:9]
	v_mfma_f32_16x16x32_bf16 v[10:13], v[136:139], v[200:203], v[10:13]
	v_mfma_f32_16x16x32_bf16 v[14:17], v[136:139], v[204:207], v[14:17]
	v_mfma_f32_16x16x32_bf16 v[18:21], v[140:143], v[188:191], v[18:21]
	v_mfma_f32_16x16x32_bf16 v[22:25], v[140:143], v[196:199], v[22:25]
	v_mfma_f32_16x16x32_bf16 v[26:29], v[140:143], v[200:203], v[26:29]
	v_mfma_f32_16x16x32_bf16 v[30:33], v[140:143], v[204:207], v[30:33]
	v_mfma_f32_16x16x32_bf16 v[34:37], v[144:147], v[188:191], v[34:37]
	v_mfma_f32_16x16x32_bf16 v[38:41], v[144:147], v[196:199], v[38:41]
	v_mfma_f32_16x16x32_bf16 v[42:45], v[144:147], v[200:203], v[42:45]
	v_mfma_f32_16x16x32_bf16 v[46:49], v[144:147], v[204:207], v[46:49]
	v_mfma_f32_16x16x32_bf16 v[50:53], v[148:151], v[188:191], v[50:53]
	v_mfma_f32_16x16x32_bf16 v[54:57], v[148:151], v[196:199], v[54:57]
	v_mfma_f32_16x16x32_bf16 v[58:61], v[148:151], v[200:203], v[58:61]
	v_mfma_f32_16x16x32_bf16 v[62:65], v[148:151], v[204:207], v[62:65]
	s_waitcnt lgkmcnt(0)
	v_mfma_f32_16x16x32_bf16 v[2:5], v[172:175], v[212:215], v[2:5]
	v_mfma_f32_16x16x32_bf16 v[6:9], v[172:175], v[216:219], v[6:9]
	v_mfma_f32_16x16x32_bf16 v[10:13], v[172:175], v[220:223], v[10:13]
	v_mfma_f32_16x16x32_bf16 v[14:17], v[172:175], v[224:227], v[14:17]
	v_mfma_f32_16x16x32_bf16 v[18:21], v[176:179], v[212:215], v[18:21]
	v_mfma_f32_16x16x32_bf16 v[22:25], v[176:179], v[216:219], v[22:25]
	v_mfma_f32_16x16x32_bf16 v[26:29], v[176:179], v[220:223], v[26:29]
	v_mfma_f32_16x16x32_bf16 v[30:33], v[176:179], v[224:227], v[30:33]
	v_mfma_f32_16x16x32_bf16 v[34:37], v[180:183], v[212:215], v[34:37]
	v_mfma_f32_16x16x32_bf16 v[38:41], v[180:183], v[216:219], v[38:41]
	v_mfma_f32_16x16x32_bf16 v[42:45], v[180:183], v[220:223], v[42:45]
	v_mfma_f32_16x16x32_bf16 v[46:49], v[180:183], v[224:227], v[46:49]
	v_mfma_f32_16x16x32_bf16 v[50:53], v[184:187], v[212:215], v[50:53]
	v_mfma_f32_16x16x32_bf16 v[54:57], v[184:187], v[216:219], v[54:57]
	v_mfma_f32_16x16x32_bf16 v[58:61], v[184:187], v[220:223], v[58:61]
	v_mfma_f32_16x16x32_bf16 v[62:65], v[184:187], v[224:227], v[62:65]
	s_setprio 0
	s_waitcnt vmcnt(6)
	s_barrier
	v_add_u32_e32 v236, s41, v232
	v_add_u32_e32 v237, s41, v233
	ds_read_b128 v[188:191], v236
	ds_read_b128 v[196:199], v236 offset:2048
	ds_read_b128 v[200:203], v236 offset:4096
	ds_read_b128 v[204:207], v236 offset:6144
	ds_read_b128 v[212:215], v237
	ds_read_b128 v[216:219], v237 offset:2048
	ds_read_b128 v[220:223], v237 offset:4096
	ds_read_b128 v[224:227], v237 offset:6144
	s_add_i32 m0, s51, 0xc000
	s_nop 0
	global_load_lds_dwordx4 v229, s[46:47]
	s_add_i32 m0, s51, 0xc400
	s_nop 0
	global_load_lds_dwordx4 v231, s[46:47]
	s_add_i32 m0, s51, 0xe000
	s_nop 0
	global_load_lds_dwordx4 v228, s[48:49]
	s_add_i32 m0, s51, 0xe400
	s_nop 0
	global_load_lds_dwordx4 v230, s[48:49]
	s_add_i32 m0, s51, 0x10000
	s_nop 0
	global_load_lds_dwordx4 v229, s[48:49]
	s_add_i32 m0, s51, 0x10400
	s_nop 0
	global_load_lds_dwordx4 v231, s[48:49]
	s_waitcnt lgkmcnt(4)
	s_setprio 1
	s_cbranch_vccz .Lgu2_ap4
	s_setprio 3
.Lgu2_ap4:
	v_mfma_f32_16x16x32_bf16 v[66:69], v[136:139], v[188:191], v[66:69]
	v_mfma_f32_16x16x32_bf16 v[70:73], v[136:139], v[196:199], v[70:73]
	v_mfma_f32_16x16x32_bf16 v[74:77], v[136:139], v[200:203], v[74:77]
	v_mfma_f32_16x16x32_bf16 v[78:81], v[136:139], v[204:207], v[78:81]
	v_mfma_f32_16x16x32_bf16 v[82:85], v[140:143], v[188:191], v[82:85]
	v_mfma_f32_16x16x32_bf16 v[86:89], v[140:143], v[196:199], v[86:89]
	v_mfma_f32_16x16x32_bf16 v[90:93], v[140:143], v[200:203], v[90:93]
	v_mfma_f32_16x16x32_bf16 v[94:97], v[140:143], v[204:207], v[94:97]
	v_mfma_f32_16x16x32_bf16 v[98:101], v[144:147], v[188:191], v[98:101]
	v_mfma_f32_16x16x32_bf16 v[102:105], v[144:147], v[196:199], v[102:105]
	v_mfma_f32_16x16x32_bf16 v[106:109], v[144:147], v[200:203], v[106:109]
	v_mfma_f32_16x16x32_bf16 v[110:113], v[144:147], v[204:207], v[110:113]
	v_mfma_f32_16x16x32_bf16 v[114:117], v[148:151], v[188:191], v[114:117]
	v_mfma_f32_16x16x32_bf16 v[118:121], v[148:151], v[196:199], v[118:121]
	v_mfma_f32_16x16x32_bf16 v[122:125], v[148:151], v[200:203], v[122:125]
	v_mfma_f32_16x16x32_bf16 v[126:129], v[148:151], v[204:207], v[126:129]
	s_waitcnt lgkmcnt(0)
	v_mfma_f32_16x16x32_bf16 v[66:69], v[172:175], v[212:215], v[66:69]
	v_mfma_f32_16x16x32_bf16 v[70:73], v[172:175], v[216:219], v[70:73]
	v_mfma_f32_16x16x32_bf16 v[74:77], v[172:175], v[220:223], v[74:77]
	v_mfma_f32_16x16x32_bf16 v[78:81], v[172:175], v[224:227], v[78:81]
	v_mfma_f32_16x16x32_bf16 v[82:85], v[176:179], v[212:215], v[82:85]
	v_mfma_f32_16x16x32_bf16 v[86:89], v[176:179], v[216:219], v[86:89]
	v_mfma_f32_16x16x32_bf16 v[90:93], v[176:179], v[220:223], v[90:93]
	v_mfma_f32_16x16x32_bf16 v[94:97], v[176:179], v[224:227], v[94:97]
	v_mfma_f32_16x16x32_bf16 v[98:101], v[180:183], v[212:215], v[98:101]
	v_mfma_f32_16x16x32_bf16 v[102:105], v[180:183], v[216:219], v[102:105]
	v_mfma_f32_16x16x32_bf16 v[106:109], v[180:183], v[220:223], v[106:109]
	v_mfma_f32_16x16x32_bf16 v[110:113], v[180:183], v[224:227], v[110:113]
	v_mfma_f32_16x16x32_bf16 v[114:117], v[184:187], v[212:215], v[114:117]
	v_mfma_f32_16x16x32_bf16 v[118:121], v[184:187], v[216:219], v[118:121]
	v_mfma_f32_16x16x32_bf16 v[122:125], v[184:187], v[220:223], v[122:125]
	v_mfma_f32_16x16x32_bf16 v[126:129], v[184:187], v[224:227], v[126:129]
	s_setprio 0
	v_add_u32_e32 v228, 0x80, v228
	v_add_u32_e32 v229, 0x80, v229
	v_add_u32_e32 v230, 0x80, v230
	v_add_u32_e32 v231, 0x80, v231
	s_waitcnt vmcnt(4)
	s_barrier
	v_add_u32_e32 v234, s24, v232
	v_add_u32_e32 v236, s30, v232
	v_add_u32_e32 v235, s24, v233
	v_add_u32_e32 v237, s30, v233
	ds_read_b128 v[136:139], v234
	ds_read_b128 v[140:143], v234 offset:2048
	ds_read_b128 v[144:147], v234 offset:4096
	ds_read_b128 v[148:151], v234 offset:6144
	ds_read_b128 v[188:191], v236
	ds_read_b128 v[196:199], v236 offset:2048
	ds_read_b128 v[200:203], v236 offset:4096
	ds_read_b128 v[204:207], v236 offset:6144
	ds_read_b128 v[172:175], v235
	ds_read_b128 v[176:179], v235 offset:2048
	ds_read_b128 v[180:183], v235 offset:4096
	ds_read_b128 v[184:187], v235 offset:6144
	ds_read_b128 v[212:215], v237
	ds_read_b128 v[216:219], v237 offset:2048
	ds_read_b128 v[220:223], v237 offset:4096
	ds_read_b128 v[224:227], v237 offset:6144
	s_mov_b32 m0, s51
	s_nop 0
	global_load_lds_dwordx4 v228, s[44:45]
	s_add_i32 m0, s51, 0x400
	s_nop 0
	global_load_lds_dwordx4 v230, s[44:45]
	s_add_i32 m0, s51, 0x2000
	s_nop 0
	global_load_lds_dwordx4 v229, s[44:45]
	s_add_i32 m0, s51, 0x2400
	s_nop 0
	global_load_lds_dwordx4 v231, s[44:45]
	s_add_i32 m0, s51, 0x4000
	s_nop 0
	global_load_lds_dwordx4 v228, s[46:47]
	s_add_i32 m0, s51, 0x4400
	s_nop 0
	global_load_lds_dwordx4 v230, s[46:47]
	s_waitcnt lgkmcnt(8)
	s_setprio 1
	s_cbranch_vccz .Lgu2_ap5
	s_setprio 3
.Lgu2_ap5:
	v_mfma_f32_16x16x32_bf16 v[2:5], v[136:139], v[188:191], v[2:5]
	v_mfma_f32_16x16x32_bf16 v[6:9], v[136:139], v[196:199], v[6:9]
	v_mfma_f32_16x16x32_bf16 v[10:13], v[136:139], v[200:203], v[10:13]
	v_mfma_f32_16x16x32_bf16 v[14:17], v[136:139], v[204:207], v[14:17]
	v_mfma_f32_16x16x32_bf16 v[18:21], v[140:143], v[188:191], v[18:21]
	v_mfma_f32_16x16x32_bf16 v[22:25], v[140:143], v[196:199], v[22:25]
	v_mfma_f32_16x16x32_bf16 v[26:29], v[140:143], v[200:203], v[26:29]
	v_mfma_f32_16x16x32_bf16 v[30:33], v[140:143], v[204:207], v[30:33]
	v_mfma_f32_16x16x32_bf16 v[34:37], v[144:147], v[188:191], v[34:37]
	v_mfma_f32_16x16x32_bf16 v[38:41], v[144:147], v[196:199], v[38:41]
	v_mfma_f32_16x16x32_bf16 v[42:45], v[144:147], v[200:203], v[42:45]
	v_mfma_f32_16x16x32_bf16 v[46:49], v[144:147], v[204:207], v[46:49]
	v_mfma_f32_16x16x32_bf16 v[50:53], v[148:151], v[188:191], v[50:53]
	v_mfma_f32_16x16x32_bf16 v[54:57], v[148:151], v[196:199], v[54:57]
	v_mfma_f32_16x16x32_bf16 v[58:61], v[148:151], v[200:203], v[58:61]
	v_mfma_f32_16x16x32_bf16 v[62:65], v[148:151], v[204:207], v[62:65]
	s_waitcnt lgkmcnt(0)
	v_mfma_f32_16x16x32_bf16 v[2:5], v[172:175], v[212:215], v[2:5]
	v_mfma_f32_16x16x32_bf16 v[6:9], v[172:175], v[216:219], v[6:9]
	v_mfma_f32_16x16x32_bf16 v[10:13], v[172:175], v[220:223], v[10:13]
	v_mfma_f32_16x16x32_bf16 v[14:17], v[172:175], v[224:227], v[14:17]
	v_mfma_f32_16x16x32_bf16 v[18:21], v[176:179], v[212:215], v[18:21]
	v_mfma_f32_16x16x32_bf16 v[22:25], v[176:179], v[216:219], v[22:25]
	v_mfma_f32_16x16x32_bf16 v[26:29], v[176:179], v[220:223], v[26:29]
	v_mfma_f32_16x16x32_bf16 v[30:33], v[176:179], v[224:227], v[30:33]
	v_mfma_f32_16x16x32_bf16 v[34:37], v[180:183], v[212:215], v[34:37]
	v_mfma_f32_16x16x32_bf16 v[38:41], v[180:183], v[216:219], v[38:41]
	v_mfma_f32_16x16x32_bf16 v[42:45], v[180:183], v[220:223], v[42:45]
	v_mfma_f32_16x16x32_bf16 v[46:49], v[180:183], v[224:227], v[46:49]
	v_mfma_f32_16x16x32_bf16 v[50:53], v[184:187], v[212:215], v[50:53]
	v_mfma_f32_16x16x32_bf16 v[54:57], v[184:187], v[216:219], v[54:57]
	v_mfma_f32_16x16x32_bf16 v[58:61], v[184:187], v[220:223], v[58:61]
	v_mfma_f32_16x16x32_bf16 v[62:65], v[184:187], v[224:227], v[62:65]
	s_setprio 0
	s_waitcnt vmcnt(6)
	s_barrier
	v_add_u32_e32 v236, s42, v232
	v_add_u32_e32 v237, s42, v233
	ds_read_b128 v[188:191], v236
	ds_read_b128 v[196:199], v236 offset:2048
	ds_read_b128 v[200:203], v236 offset:4096
	ds_read_b128 v[204:207], v236 offset:6144
	ds_read_b128 v[212:215], v237
	ds_read_b128 v[216:219], v237 offset:2048
	ds_read_b128 v[220:223], v237 offset:4096
	ds_read_b128 v[224:227], v237 offset:6144
	s_add_i32 m0, s51, 0x6000
	s_nop 0
	global_load_lds_dwordx4 v229, s[46:47]
	s_add_i32 m0, s51, 0x6400
	s_nop 0
	global_load_lds_dwordx4 v231, s[46:47]
	s_add_i32 m0, s51, 0x8000
	s_nop 0
	global_load_lds_dwordx4 v228, s[48:49]
	s_add_i32 m0, s51, 0x8400
	s_nop 0
	global_load_lds_dwordx4 v230, s[48:49]
	s_add_i32 m0, s51, 0xa000
	s_nop 0
	global_load_lds_dwordx4 v229, s[48:49]
	s_add_i32 m0, s51, 0xa400
	s_nop 0
	global_load_lds_dwordx4 v231, s[48:49]
	s_waitcnt lgkmcnt(4)
	s_setprio 1
	s_cbranch_vccz .Lgu2_ap6
	s_setprio 3
.Lgu2_ap6:
	v_mfma_f32_16x16x32_bf16 v[66:69], v[136:139], v[188:191], v[66:69]
	v_mfma_f32_16x16x32_bf16 v[70:73], v[136:139], v[196:199], v[70:73]
	v_mfma_f32_16x16x32_bf16 v[74:77], v[136:139], v[200:203], v[74:77]
	v_mfma_f32_16x16x32_bf16 v[78:81], v[136:139], v[204:207], v[78:81]
	v_mfma_f32_16x16x32_bf16 v[82:85], v[140:143], v[188:191], v[82:85]
	v_mfma_f32_16x16x32_bf16 v[86:89], v[140:143], v[196:199], v[86:89]
	v_mfma_f32_16x16x32_bf16 v[90:93], v[140:143], v[200:203], v[90:93]
	v_mfma_f32_16x16x32_bf16 v[94:97], v[140:143], v[204:207], v[94:97]
	v_mfma_f32_16x16x32_bf16 v[98:101], v[144:147], v[188:191], v[98:101]
	v_mfma_f32_16x16x32_bf16 v[102:105], v[144:147], v[196:199], v[102:105]
	v_mfma_f32_16x16x32_bf16 v[106:109], v[144:147], v[200:203], v[106:109]
	v_mfma_f32_16x16x32_bf16 v[110:113], v[144:147], v[204:207], v[110:113]
	v_mfma_f32_16x16x32_bf16 v[114:117], v[148:151], v[188:191], v[114:117]
	v_mfma_f32_16x16x32_bf16 v[118:121], v[148:151], v[196:199], v[118:121]
	v_mfma_f32_16x16x32_bf16 v[122:125], v[148:151], v[200:203], v[122:125]
	v_mfma_f32_16x16x32_bf16 v[126:129], v[148:151], v[204:207], v[126:129]
	s_waitcnt lgkmcnt(0)
	v_mfma_f32_16x16x32_bf16 v[66:69], v[172:175], v[212:215], v[66:69]
	v_mfma_f32_16x16x32_bf16 v[70:73], v[172:175], v[216:219], v[70:73]
	v_mfma_f32_16x16x32_bf16 v[74:77], v[172:175], v[220:223], v[74:77]
	v_mfma_f32_16x16x32_bf16 v[78:81], v[172:175], v[224:227], v[78:81]
	v_mfma_f32_16x16x32_bf16 v[82:85], v[176:179], v[212:215], v[82:85]
	v_mfma_f32_16x16x32_bf16 v[86:89], v[176:179], v[216:219], v[86:89]
	v_mfma_f32_16x16x32_bf16 v[90:93], v[176:179], v[220:223], v[90:93]
	v_mfma_f32_16x16x32_bf16 v[94:97], v[176:179], v[224:227], v[94:97]
	v_mfma_f32_16x16x32_bf16 v[98:101], v[180:183], v[212:215], v[98:101]
	v_mfma_f32_16x16x32_bf16 v[102:105], v[180:183], v[216:219], v[102:105]
	v_mfma_f32_16x16x32_bf16 v[106:109], v[180:183], v[220:223], v[106:109]
	v_mfma_f32_16x16x32_bf16 v[110:113], v[180:183], v[224:227], v[110:113]
	v_mfma_f32_16x16x32_bf16 v[114:117], v[184:187], v[212:215], v[114:117]
	v_mfma_f32_16x16x32_bf16 v[118:121], v[184:187], v[216:219], v[118:121]
	v_mfma_f32_16x16x32_bf16 v[122:125], v[184:187], v[220:223], v[122:125]
	v_mfma_f32_16x16x32_bf16 v[126:129], v[184:187], v[224:227], v[126:129]
	s_setprio 0
	v_add_u32_e32 v228, 0x80, v228
	v_add_u32_e32 v229, 0x80, v229
	v_add_u32_e32 v230, 0x80, v230
	v_add_u32_e32 v231, 0x80, v231
	s_waitcnt vmcnt(4)
	s_barrier
	s_add_i32 s52, s52, 1
	s_cmp_lt_u32 s52, 10
	s_cbranch_scc1 .Lgu2_loop
	v_add_u32_e32 v234, s22, v232
	v_add_u32_e32 v236, s28, v232
	v_add_u32_e32 v235, s22, v233
	v_add_u32_e32 v237, s28, v233
	ds_read_b128 v[136:139], v234
	ds_read_b128 v[140:143], v234 offset:2048
	ds_read_b128 v[144:147], v234 offset:4096
	ds_read_b128 v[148:151], v234 offset:6144
	ds_read_b128 v[188:191], v236
	ds_read_b128 v[196:199], v236 offset:2048
	ds_read_b128 v[200:203], v236 offset:4096
	ds_read_b128 v[204:207], v236 offset:6144
	ds_read_b128 v[172:175], v235
	ds_read_b128 v[176:179], v235 offset:2048
	ds_read_b128 v[180:183], v235 offset:4096
	ds_read_b128 v[184:187], v235 offset:6144
	ds_read_b128 v[212:215], v237
	ds_read_b128 v[216:219], v237 offset:2048
	ds_read_b128 v[220:223], v237 offset:4096
	ds_read_b128 v[224:227], v237 offset:6144
	s_add_i32 m0, s51, 0xc000
	s_nop 0
	global_load_lds_dwordx4 v228, s[44:45]
	s_add_i32 m0, s51, 0xc400
	s_nop 0
	global_load_lds_dwordx4 v230, s[44:45]
	s_add_i32 m0, s51, 0xe000
	s_nop 0
	global_load_lds_dwordx4 v229, s[44:45]
	s_add_i32 m0, s51, 0xe400
	s_nop 0
	global_load_lds_dwordx4 v231, s[44:45]
	s_add_i32 m0, s51, 0x10000
	s_nop 0
	global_load_lds_dwordx4 v228, s[46:47]
	s_add_i32 m0, s51, 0x10400
	s_nop 0
	global_load_lds_dwordx4 v230, s[46:47]
	s_waitcnt lgkmcnt(8)
	s_setprio 1
	s_cbranch_vccz .Lgu2_ap7
	s_setprio 3
.Lgu2_ap7:
	v_mfma_f32_16x16x32_bf16 v[2:5], v[136:139], v[188:191], v[2:5]
	v_mfma_f32_16x16x32_bf16 v[6:9], v[136:139], v[196:199], v[6:9]
	v_mfma_f32_16x16x32_bf16 v[10:13], v[136:139], v[200:203], v[10:13]
	v_mfma_f32_16x16x32_bf16 v[14:17], v[136:139], v[204:207], v[14:17]
	v_mfma_f32_16x16x32_bf16 v[18:21], v[140:143], v[188:191], v[18:21]
	v_mfma_f32_16x16x32_bf16 v[22:25], v[140:143], v[196:199], v[22:25]
	v_mfma_f32_16x16x32_bf16 v[26:29], v[140:143], v[200:203], v[26:29]
	v_mfma_f32_16x16x32_bf16 v[30:33], v[140:143], v[204:207], v[30:33]
	v_mfma_f32_16x16x32_bf16 v[34:37], v[144:147], v[188:191], v[34:37]
	v_mfma_f32_16x16x32_bf16 v[38:41], v[144:147], v[196:199], v[38:41]
	v_mfma_f32_16x16x32_bf16 v[42:45], v[144:147], v[200:203], v[42:45]
	v_mfma_f32_16x16x32_bf16 v[46:49], v[144:147], v[204:207], v[46:49]
	v_mfma_f32_16x16x32_bf16 v[50:53], v[148:151], v[188:191], v[50:53]
	v_mfma_f32_16x16x32_bf16 v[54:57], v[148:151], v[196:199], v[54:57]
	v_mfma_f32_16x16x32_bf16 v[58:61], v[148:151], v[200:203], v[58:61]
	v_mfma_f32_16x16x32_bf16 v[62:65], v[148:151], v[204:207], v[62:65]
	s_waitcnt lgkmcnt(0)
	v_mfma_f32_16x16x32_bf16 v[2:5], v[172:175], v[212:215], v[2:5]
	v_mfma_f32_16x16x32_bf16 v[6:9], v[172:175], v[216:219], v[6:9]
	v_mfma_f32_16x16x32_bf16 v[10:13], v[172:175], v[220:223], v[10:13]
	v_mfma_f32_16x16x32_bf16 v[14:17], v[172:175], v[224:227], v[14:17]
	v_mfma_f32_16x16x32_bf16 v[18:21], v[176:179], v[212:215], v[18:21]
	v_mfma_f32_16x16x32_bf16 v[22:25], v[176:179], v[216:219], v[22:25]
	v_mfma_f32_16x16x32_bf16 v[26:29], v[176:179], v[220:223], v[26:29]
	v_mfma_f32_16x16x32_bf16 v[30:33], v[176:179], v[224:227], v[30:33]
	v_mfma_f32_16x16x32_bf16 v[34:37], v[180:183], v[212:215], v[34:37]
	v_mfma_f32_16x16x32_bf16 v[38:41], v[180:183], v[216:219], v[38:41]
	v_mfma_f32_16x16x32_bf16 v[42:45], v[180:183], v[220:223], v[42:45]
	v_mfma_f32_16x16x32_bf16 v[46:49], v[180:183], v[224:227], v[46:49]
	v_mfma_f32_16x16x32_bf16 v[50:53], v[184:187], v[212:215], v[50:53]
	v_mfma_f32_16x16x32_bf16 v[54:57], v[184:187], v[216:219], v[54:57]
	v_mfma_f32_16x16x32_bf16 v[58:61], v[184:187], v[220:223], v[58:61]
	v_mfma_f32_16x16x32_bf16 v[62:65], v[184:187], v[224:227], v[62:65]
	s_setprio 0
	s_waitcnt vmcnt(6)
	s_barrier
	v_add_u32_e32 v236, s40, v232
	v_add_u32_e32 v237, s40, v233
	ds_read_b128 v[188:191], v236
	ds_read_b128 v[196:199], v236 offset:2048
	ds_read_b128 v[200:203], v236 offset:4096
	ds_read_b128 v[204:207], v236 offset:6144
	ds_read_b128 v[212:215], v237
	ds_read_b128 v[216:219], v237 offset:2048
	ds_read_b128 v[220:223], v237 offset:4096
	ds_read_b128 v[224:227], v237 offset:6144
	s_mov_b32 m0, s51
	s_nop 0
	global_load_lds_dwordx4 v229, s[46:47]
	s_add_i32 m0, s51, 0x400
	s_nop 0
	global_load_lds_dwordx4 v231, s[46:47]
	s_add_i32 m0, s51, 0x2000
	s_nop 0
	global_load_lds_dwordx4 v228, s[48:49]
	s_add_i32 m0, s51, 0x2400
	s_nop 0
	global_load_lds_dwordx4 v230, s[48:49]
	s_add_i32 m0, s51, 0x4000
	s_nop 0
	global_load_lds_dwordx4 v229, s[48:49]
	s_add_i32 m0, s51, 0x4400
	s_nop 0
	global_load_lds_dwordx4 v231, s[48:49]
	s_waitcnt lgkmcnt(4)
	s_setprio 1
	s_cbranch_vccz .Lgu2_ap8
	s_setprio 3
.Lgu2_ap8:
	v_mfma_f32_16x16x32_bf16 v[66:69], v[136:139], v[188:191], v[66:69]
	v_mfma_f32_16x16x32_bf16 v[70:73], v[136:139], v[196:199], v[70:73]
	v_mfma_f32_16x16x32_bf16 v[74:77], v[136:139], v[200:203], v[74:77]
	v_mfma_f32_16x16x32_bf16 v[78:81], v[136:139], v[204:207], v[78:81]
	v_mfma_f32_16x16x32_bf16 v[82:85], v[140:143], v[188:191], v[82:85]
	v_mfma_f32_16x16x32_bf16 v[86:89], v[140:143], v[196:199], v[86:89]
	v_mfma_f32_16x16x32_bf16 v[90:93], v[140:143], v[200:203], v[90:93]
	v_mfma_f32_16x16x32_bf16 v[94:97], v[140:143], v[204:207], v[94:97]
	v_mfma_f32_16x16x32_bf16 v[98:101], v[144:147], v[188:191], v[98:101]
	v_mfma_f32_16x16x32_bf16 v[102:105], v[144:147], v[196:199], v[102:105]
	v_mfma_f32_16x16x32_bf16 v[106:109], v[144:147], v[200:203], v[106:109]
	v_mfma_f32_16x16x32_bf16 v[110:113], v[144:147], v[204:207], v[110:113]
	v_mfma_f32_16x16x32_bf16 v[114:117], v[148:151], v[188:191], v[114:117]
	v_mfma_f32_16x16x32_bf16 v[118:121], v[148:151], v[196:199], v[118:121]
	v_mfma_f32_16x16x32_bf16 v[122:125], v[148:151], v[200:203], v[122:125]
	v_mfma_f32_16x16x32_bf16 v[126:129], v[148:151], v[204:207], v[126:129]
	s_waitcnt lgkmcnt(0)
	v_mfma_f32_16x16x32_bf16 v[66:69], v[172:175], v[212:215], v[66:69]
	v_mfma_f32_16x16x32_bf16 v[70:73], v[172:175], v[216:219], v[70:73]
	v_mfma_f32_16x16x32_bf16 v[74:77], v[172:175], v[220:223], v[74:77]
	v_mfma_f32_16x16x32_bf16 v[78:81], v[172:175], v[224:227], v[78:81]
	v_mfma_f32_16x16x32_bf16 v[82:85], v[176:179], v[212:215], v[82:85]
	v_mfma_f32_16x16x32_bf16 v[86:89], v[176:179], v[216:219], v[86:89]
	v_mfma_f32_16x16x32_bf16 v[90:93], v[176:179], v[220:223], v[90:93]
	v_mfma_f32_16x16x32_bf16 v[94:97], v[176:179], v[224:227], v[94:97]
	v_mfma_f32_16x16x32_bf16 v[98:101], v[180:183], v[212:215], v[98:101]
	v_mfma_f32_16x16x32_bf16 v[102:105], v[180:183], v[216:219], v[102:105]
	v_mfma_f32_16x16x32_bf16 v[106:109], v[180:183], v[220:223], v[106:109]
	v_mfma_f32_16x16x32_bf16 v[110:113], v[180:183], v[224:227], v[110:113]
	v_mfma_f32_16x16x32_bf16 v[114:117], v[184:187], v[212:215], v[114:117]
	v_mfma_f32_16x16x32_bf16 v[118:121], v[184:187], v[216:219], v[118:121]
	v_mfma_f32_16x16x32_bf16 v[122:125], v[184:187], v[220:223], v[122:125]
	v_mfma_f32_16x16x32_bf16 v[126:129], v[184:187], v[224:227], v[126:129]
	s_setprio 0
	v_add_u32_e32 v228, 0x80, v228
	v_add_u32_e32 v229, 0x80, v229
	v_add_u32_e32 v230, 0x80, v230
	v_add_u32_e32 v231, 0x80, v231
	s_waitcnt vmcnt(4)
	s_barrier
	v_add_u32_e32 v234, s23, v232
	v_add_u32_e32 v236, s29, v232
	v_add_u32_e32 v235, s23, v233
	v_add_u32_e32 v237, s29, v233
	ds_read_b128 v[136:139], v234
	ds_read_b128 v[140:143], v234 offset:2048
	ds_read_b128 v[144:147], v234 offset:4096
	ds_read_b128 v[148:151], v234 offset:6144
	ds_read_b128 v[188:191], v236
	ds_read_b128 v[196:199], v236 offset:2048
	ds_read_b128 v[200:203], v236 offset:4096
	ds_read_b128 v[204:207], v236 offset:6144
	ds_read_b128 v[172:175], v235
	ds_read_b128 v[176:179], v235 offset:2048
	ds_read_b128 v[180:183], v235 offset:4096
	ds_read_b128 v[184:187], v235 offset:6144
	ds_read_b128 v[212:215], v237
	ds_read_b128 v[216:219], v237 offset:2048
	ds_read_b128 v[220:223], v237 offset:4096
	ds_read_b128 v[224:227], v237 offset:6144
	s_waitcnt lgkmcnt(8)
	s_setprio 1
	s_cbranch_vccz .Lgu2_ap9
	s_setprio 3
.Lgu2_ap9:
	v_mfma_f32_16x16x32_bf16 v[2:5], v[136:139], v[188:191], v[2:5]
	v_mfma_f32_16x16x32_bf16 v[6:9], v[136:139], v[196:199], v[6:9]
	v_mfma_f32_16x16x32_bf16 v[10:13], v[136:139], v[200:203], v[10:13]
	v_mfma_f32_16x16x32_bf16 v[14:17], v[136:139], v[204:207], v[14:17]
	v_mfma_f32_16x16x32_bf16 v[18:21], v[140:143], v[188:191], v[18:21]
	v_mfma_f32_16x16x32_bf16 v[22:25], v[140:143], v[196:199], v[22:25]
	v_mfma_f32_16x16x32_bf16 v[26:29], v[140:143], v[200:203], v[26:29]
	v_mfma_f32_16x16x32_bf16 v[30:33], v[140:143], v[204:207], v[30:33]
	v_mfma_f32_16x16x32_bf16 v[34:37], v[144:147], v[188:191], v[34:37]
	v_mfma_f32_16x16x32_bf16 v[38:41], v[144:147], v[196:199], v[38:41]
	v_mfma_f32_16x16x32_bf16 v[42:45], v[144:147], v[200:203], v[42:45]
	v_mfma_f32_16x16x32_bf16 v[46:49], v[144:147], v[204:207], v[46:49]
	v_mfma_f32_16x16x32_bf16 v[50:53], v[148:151], v[188:191], v[50:53]
	v_mfma_f32_16x16x32_bf16 v[54:57], v[148:151], v[196:199], v[54:57]
	v_mfma_f32_16x16x32_bf16 v[58:61], v[148:151], v[200:203], v[58:61]
	v_mfma_f32_16x16x32_bf16 v[62:65], v[148:151], v[204:207], v[62:65]
	s_waitcnt lgkmcnt(0)
	v_mfma_f32_16x16x32_bf16 v[2:5], v[172:175], v[212:215], v[2:5]
	v_mfma_f32_16x16x32_bf16 v[6:9], v[172:175], v[216:219], v[6:9]
	v_mfma_f32_16x16x32_bf16 v[10:13], v[172:175], v[220:223], v[10:13]
	v_mfma_f32_16x16x32_bf16 v[14:17], v[172:175], v[224:227], v[14:17]
	v_mfma_f32_16x16x32_bf16 v[18:21], v[176:179], v[212:215], v[18:21]
	v_mfma_f32_16x16x32_bf16 v[22:25], v[176:179], v[216:219], v[22:25]
	v_mfma_f32_16x16x32_bf16 v[26:29], v[176:179], v[220:223], v[26:29]
	v_mfma_f32_16x16x32_bf16 v[30:33], v[176:179], v[224:227], v[30:33]
	v_mfma_f32_16x16x32_bf16 v[34:37], v[180:183], v[212:215], v[34:37]
	v_mfma_f32_16x16x32_bf16 v[38:41], v[180:183], v[216:219], v[38:41]
	v_mfma_f32_16x16x32_bf16 v[42:45], v[180:183], v[220:223], v[42:45]
	v_mfma_f32_16x16x32_bf16 v[46:49], v[180:183], v[224:227], v[46:49]
	v_mfma_f32_16x16x32_bf16 v[50:53], v[184:187], v[212:215], v[50:53]
	v_mfma_f32_16x16x32_bf16 v[54:57], v[184:187], v[216:219], v[54:57]
	v_mfma_f32_16x16x32_bf16 v[58:61], v[184:187], v[220:223], v[58:61]
	v_mfma_f32_16x16x32_bf16 v[62:65], v[184:187], v[224:227], v[62:65]
	s_setprio 0
	s_waitcnt vmcnt(0)
	s_barrier
	v_add_u32_e32 v236, s41, v232
	v_add_u32_e32 v237, s41, v233
	ds_read_b128 v[188:191], v236
	ds_read_b128 v[196:199], v236 offset:2048
	ds_read_b128 v[200:203], v236 offset:4096
	ds_read_b128 v[204:207], v236 offset:6144
	ds_read_b128 v[212:215], v237
	ds_read_b128 v[216:219], v237 offset:2048
	ds_read_b128 v[220:223], v237 offset:4096
	ds_read_b128 v[224:227], v237 offset:6144
	s_waitcnt lgkmcnt(4)
	s_setprio 1
	s_cbranch_vccz .Lgu2_ap10
	s_setprio 3
.Lgu2_ap10:
	v_mfma_f32_16x16x32_bf16 v[66:69], v[136:139], v[188:191], v[66:69]
	v_mfma_f32_16x16x32_bf16 v[70:73], v[136:139], v[196:199], v[70:73]
	v_mfma_f32_16x16x32_bf16 v[74:77], v[136:139], v[200:203], v[74:77]
	v_mfma_f32_16x16x32_bf16 v[78:81], v[136:139], v[204:207], v[78:81]
	v_mfma_f32_16x16x32_bf16 v[82:85], v[140:143], v[188:191], v[82:85]
	v_mfma_f32_16x16x32_bf16 v[86:89], v[140:143], v[196:199], v[86:89]
	v_mfma_f32_16x16x32_bf16 v[90:93], v[140:143], v[200:203], v[90:93]
	v_mfma_f32_16x16x32_bf16 v[94:97], v[140:143], v[204:207], v[94:97]
	v_mfma_f32_16x16x32_bf16 v[98:101], v[144:147], v[188:191], v[98:101]
	v_mfma_f32_16x16x32_bf16 v[102:105], v[144:147], v[196:199], v[102:105]
	v_mfma_f32_16x16x32_bf16 v[106:109], v[144:147], v[200:203], v[106:109]
	v_mfma_f32_16x16x32_bf16 v[110:113], v[144:147], v[204:207], v[110:113]
	v_mfma_f32_16x16x32_bf16 v[114:117], v[148:151], v[188:191], v[114:117]
	v_mfma_f32_16x16x32_bf16 v[118:121], v[148:151], v[196:199], v[118:121]
	v_mfma_f32_16x16x32_bf16 v[122:125], v[148:151], v[200:203], v[122:125]
	v_mfma_f32_16x16x32_bf16 v[126:129], v[148:151], v[204:207], v[126:129]
	s_waitcnt lgkmcnt(0)
	v_mfma_f32_16x16x32_bf16 v[66:69], v[172:175], v[212:215], v[66:69]
	v_mfma_f32_16x16x32_bf16 v[70:73], v[172:175], v[216:219], v[70:73]
	v_mfma_f32_16x16x32_bf16 v[74:77], v[172:175], v[220:223], v[74:77]
	v_mfma_f32_16x16x32_bf16 v[78:81], v[172:175], v[224:227], v[78:81]
	v_mfma_f32_16x16x32_bf16 v[82:85], v[176:179], v[212:215], v[82:85]
	v_mfma_f32_16x16x32_bf16 v[86:89], v[176:179], v[216:219], v[86:89]
	v_mfma_f32_16x16x32_bf16 v[90:93], v[176:179], v[220:223], v[90:93]
	v_mfma_f32_16x16x32_bf16 v[94:97], v[176:179], v[224:227], v[94:97]
	v_mfma_f32_16x16x32_bf16 v[98:101], v[180:183], v[212:215], v[98:101]
	v_mfma_f32_16x16x32_bf16 v[102:105], v[180:183], v[216:219], v[102:105]
	v_mfma_f32_16x16x32_bf16 v[106:109], v[180:183], v[220:223], v[106:109]
	v_mfma_f32_16x16x32_bf16 v[110:113], v[180:183], v[224:227], v[110:113]
	v_mfma_f32_16x16x32_bf16 v[114:117], v[184:187], v[212:215], v[114:117]
	v_mfma_f32_16x16x32_bf16 v[118:121], v[184:187], v[216:219], v[118:121]
	v_mfma_f32_16x16x32_bf16 v[122:125], v[184:187], v[220:223], v[122:125]
	v_mfma_f32_16x16x32_bf16 v[126:129], v[184:187], v[224:227], v[126:129]
	s_setprio 0
	s_nop 7
	s_barrier
	s_mul_i32 s43, s53, 0x2c80
	s_add_i32 s43, s43, s54
	s_add_i32 s55, s55, 1
	s_cmp_lt_u32 s55, 5
	s_cbranch_scc0 .Lgu2_nonext
	s_load_dwordx2 s[44:45], s[12:13], 0x160
	s_load_dwordx2 s[46:47], s[12:13], 0x130
	s_bfe_u32 s53, s21, 0x30006
	s_lshl_b32 s53, s53, 3
	s_and_b32 s56, s21, 7
	s_or_b32 s53, s53, s56
	s_lshl_b32 s53, s53, 7
	s_bfe_u32 s54, s21, 0x30003
	s_lshl_b32 s56, s55, 4
	s_add_i32 s54, s54, s56
	s_lshl_b32 s54, s54, 7
	v_lshrrev_b32_e32 v196, 6, v131
	v_and_b32_e32 v197, 63, v131
	s_nop 0
	v_readfirstlane_b32 s50, v196
	v_lshrrev_b32_e32 v196, 3, v197
	v_lshrrev_b32_e32 v198, 4, v197
	v_and_b32_e32 v199, 7, v197
	s_movk_i32 s56, 0x1080
	v_xor_b32_e32 v200, v199, v198
	v_lshlrev_b32_e32 v200, 4, v200
	v_mad_u32_u24 v228, v196, s56, v200
	v_or_b32_e32 v198, 4, v198
	v_xor_b32_e32 v200, v199, v198
	v_lshlrev_b32_e32 v200, 4, v200
	v_add_u32_e32 v196, 8, v196
	v_mad_u32_u24 v230, v196, s56, v200
	v_add_u32_e32 v229, 0x42000, v228
	v_add_u32_e32 v231, 0x42000, v230
	v_and_b32_e32 v196, 15, v197
	v_lshrrev_b32_e32 v198, 4, v197
	v_bfe_u32 v199, v197, 1, 3
	v_xor_b32_e32 v199, v198, v199
	v_lshlrev_b32_e32 v199, 4, v199
	v_lshl_or_b32 v232, v196, 7, v199
	v_xor_b32_e32 v233, 64, v232
	s_lshr_b32 s56, s50, 1
	s_and_b32 s57, s50, 1
	s_mul_i32 s0, s56, 64*528
	s_lshl_b32 s52, s57, 8
	s_add_i32 s0, s0, s52
	s_add_i32 s0, s0, 16
	v_mul_u32_u24_e32 v198, 4*528, v198
	v_lshl_add_u32 v198, v196, 2, v198
	v_add_u32_e32 v238, s0, v198
	s_add_i32 s22, s56, 0
	s_lshl_b32 s22, s22, 13
	s_add_i32 s22, s22, 16
	s_add_i32 s28, s57, 2
	s_lshl_b32 s28, s28, 13
	s_add_i32 s28, s28, 16
	s_add_i32 s40, s57, 4
	s_lshl_b32 s40, s40, 13
	s_add_i32 s40, s40, 16
	s_add_i32 s23, s56, 6
	s_lshl_b32 s23, s23, 13
	s_add_i32 s23, s23, 16
	s_add_i32 s29, s57, 8
	s_cmp_ge_u32 s29, 9
	s_cselect_b32 s0, 9, 0
	s_sub_i32 s29, s29, s0
	s_lshl_b32 s29, s29, 13
	s_add_i32 s29, s29, 16
	s_add_i32 s41, s57, 1
	s_lshl_b32 s41, s41, 13
	s_add_i32 s41, s41, 16
	s_add_i32 s24, s56, 3
	s_lshl_b32 s24, s24, 13
	s_add_i32 s24, s24, 16
	s_add_i32 s30, s57, 5
	s_lshl_b32 s30, s30, 13
	s_add_i32 s30, s30, 16
	s_add_i32 s42, s57, 7
	s_lshl_b32 s42, s42, 13
	s_add_i32 s42, s42, 16
	s_lshl_b32 s56, s50, 4
	s_add_i32 s57, s53, s56
	s_add_i32 s56, s54, s56
	s_mul_i32 s57, s57, 0x1080
	s_mul_i32 s56, s56, 0x1080
	s_waitcnt lgkmcnt(0)
	s_add_u32 s44, s44, s57
	s_addc_u32 s45, s45, 0
	s_add_u32 s46, s46, s56
	s_addc_u32 s47, s47, 0
	s_add_u32 s48, s46, 0x420000
	s_addc_u32 s49, s47, 0
	s_lshl_b32 s51, s50, 11
	s_add_i32 s51, s51, 16
	s_mov_b32 m0, s51
	s_nop 0
	global_load_lds_dwordx4 v228, s[44:45]
	s_add_i32 m0, s51, 0x400
	s_nop 0
	global_load_lds_dwordx4 v230, s[44:45]
	s_add_i32 m0, s51, 0x2000
	s_nop 0
	global_load_lds_dwordx4 v229, s[44:45]
	s_add_i32 m0, s51, 0x2400
	s_nop 0
	global_load_lds_dwordx4 v231, s[44:45]
	s_add_i32 m0, s51, 0x4000
	s_nop 0
	global_load_lds_dwordx4 v228, s[46:47]
	s_add_i32 m0, s51, 0x4400
	s_nop 0
	global_load_lds_dwordx4 v230, s[46:47]
	s_add_i32 m0, s51, 0x6000
	s_nop 0
	global_load_lds_dwordx4 v229, s[46:47]
	s_add_i32 m0, s51, 0x6400
	s_nop 0
	global_load_lds_dwordx4 v231, s[46:47]
	s_add_i32 m0, s51, 0x8000
	s_nop 0
	global_load_lds_dwordx4 v228, s[48:49]
	s_add_i32 m0, s51, 0x8400
	s_nop 0
	global_load_lds_dwordx4 v230, s[48:49]
	s_add_i32 m0, s51, 0xa000
	s_nop 0
	global_load_lds_dwordx4 v229, s[48:49]
	s_add_i32 m0, s51, 0xa400
	s_nop 0
	global_load_lds_dwordx4 v231, s[48:49]
	v_add_u32_e32 v228, 0x80, v228
	v_add_u32_e32 v229, 0x80, v229
	v_add_u32_e32 v230, 0x80, v230
	v_add_u32_e32 v231, 0x80, v231
.Lgu2_nonext:
	s_load_dwordx2 s[58:59], s[12:13], 0x180
	v_mov_b32_e32 v241, 0x3a000000
	v_mov_b32_e32 v242, 0x358637bd
	v_fma_f32 v152, v152, v241, v242
	v_fma_f32 v153, v153, v241, v242
	v_fma_f32 v154, v154, v241, v242
	v_fma_f32 v155, v155, v241, v242
	v_fma_f32 v244, v244, v241, v242
	v_fma_f32 v245, v245, v241, v242
	v_fma_f32 v246, v246, v241, v242
	v_fma_f32 v247, v247, v241, v242
	v_fma_f32 v248, v248, v241, v242
	v_fma_f32 v249, v249, v241, v242
	v_fma_f32 v250, v250, v241, v242
	v_fma_f32 v251, v251, v241, v242
	v_fma_f32 v252, v252, v241, v242
	v_fma_f32 v253, v253, v241, v242
	v_fma_f32 v254, v254, v241, v242
	v_fma_f32 v255, v255, v241, v242
	v_rsq_f32_e32 v152, v152
	v_rsq_f32_e32 v153, v153
	v_rsq_f32_e32 v154, v154
	v_rsq_f32_e32 v155, v155
	v_rsq_f32_e32 v244, v244
	v_rsq_f32_e32 v245, v245
	v_rsq_f32_e32 v246, v246
	v_rsq_f32_e32 v247, v247
	v_rsq_f32_e32 v248, v248
	v_rsq_f32_e32 v249, v249
	v_rsq_f32_e32 v250, v250
	v_rsq_f32_e32 v251, v251
	v_rsq_f32_e32 v252, v252
	v_rsq_f32_e32 v253, v253
	v_rsq_f32_e32 v254, v254
	v_rsq_f32_e32 v255, v255
	v_and_b32_e32 v241, 63, v131
	v_lshrrev_b32_e32 v242, 4, v241
	v_and_b32_e32 v241, 15, v241
	s_lshr_b32 s56, s50, 1
	s_and_b32 s57, s50, 1
	s_mul_i32 s56, s56, 64*144
	s_lshl_b32 s57, s57, 6
	s_add_i32 s56, s56, s57
	s_add_i32 s56, s56, 49168
	v_mul_u32_u24_e32 v242, 4*144, v242
	v_lshl_add_u32 v242, v241, 1, v242
	v_add_u32_e32 v188, s56, v242
	v_lshrrev_b32_e32 v241, 3, v131
	v_and_b32_e32 v242, 7, v131
	v_lshlrev_b32_e32 v242, 4, v242
	v_mul_u32_u24_e32 v189, 144, v241
	s_mov_b32 s57, 0xc010
	v_add3_u32 v189, v189, v242, s57
	s_movk_i32 s56, 0x2c80
	v_mad_u32_u24 v243, v241, s56, v242
	s_mov_b32 s56, s43
	s_waitcnt lgkmcnt(0)
	s_add_u32 s58, s58, s56
	s_addc_u32 s59, s59, 0
	v_mul_f32_e32 v2, v2, v152
	v_mul_f32_e32 v6, v6, v152
	v_mul_f32_e32 v10, v10, v152
	v_mul_f32_e32 v14, v14, v152
	v_mul_f32_e32 v136, 0xbfb8aa3b, v2
	v_mul_f32_e32 v137, 0xbfb8aa3b, v6
	v_exp_f32_e32 v136, v136
	v_exp_f32_e32 v137, v137
	v_mul_f32_e32 v10, v10, v2
	v_mul_f32_e32 v14, v14, v6
	v_add_f32_e32 v136, 1.0, v136
	v_add_f32_e32 v137, 1.0, v137
	v_rcp_f32_e32 v136, v136
	v_rcp_f32_e32 v137, v137
	s_nop 0
	v_mul_f32_e32 v10, v10, v136
	v_mul_f32_e32 v14, v14, v137
	v_cvt_pk_bf16_f32 v10, v10, v14
	ds_write_b16 v188, v10
	ds_write_b16_d16_hi v188, v10 offset:32
	v_mul_f32_e32 v3, v3, v153
	v_mul_f32_e32 v7, v7, v153
	v_mul_f32_e32 v11, v11, v153
	v_mul_f32_e32 v15, v15, v153
	v_mul_f32_e32 v136, 0xbfb8aa3b, v3
	v_mul_f32_e32 v137, 0xbfb8aa3b, v7
	v_exp_f32_e32 v136, v136
	v_exp_f32_e32 v137, v137
	v_mul_f32_e32 v11, v11, v3
	v_mul_f32_e32 v15, v15, v7
	v_add_f32_e32 v136, 1.0, v136
	v_add_f32_e32 v137, 1.0, v137
	v_rcp_f32_e32 v136, v136
	v_rcp_f32_e32 v137, v137
	s_nop 0
	v_mul_f32_e32 v11, v11, v136
	v_mul_f32_e32 v15, v15, v137
	v_cvt_pk_bf16_f32 v11, v11, v15
	ds_write_b16 v188, v11 offset:144
	ds_write_b16_d16_hi v188, v11 offset:176
	v_mul_f32_e32 v4, v4, v154
	v_mul_f32_e32 v8, v8, v154
	v_mul_f32_e32 v12, v12, v154
	v_mul_f32_e32 v16, v16, v154
	v_mul_f32_e32 v136, 0xbfb8aa3b, v4
	v_mul_f32_e32 v137, 0xbfb8aa3b, v8
	v_exp_f32_e32 v136, v136
	v_exp_f32_e32 v137, v137
	v_mul_f32_e32 v12, v12, v4
	v_mul_f32_e32 v16, v16, v8
	v_add_f32_e32 v136, 1.0, v136
	v_add_f32_e32 v137, 1.0, v137
	v_rcp_f32_e32 v136, v136
	v_rcp_f32_e32 v137, v137
	s_nop 0
	v_mul_f32_e32 v12, v12, v136
	v_mul_f32_e32 v16, v16, v137
	v_cvt_pk_bf16_f32 v12, v12, v16
	ds_write_b16 v188, v12 offset:288
	ds_write_b16_d16_hi v188, v12 offset:320
	v_mul_f32_e32 v5, v5, v155
	v_mul_f32_e32 v9, v9, v155
	v_mul_f32_e32 v13, v13, v155
	v_mul_f32_e32 v17, v17, v155
	v_mul_f32_e32 v136, 0xbfb8aa3b, v5
	v_mul_f32_e32 v137, 0xbfb8aa3b, v9
	v_exp_f32_e32 v136, v136
	v_exp_f32_e32 v137, v137
	v_mul_f32_e32 v13, v13, v5
	v_mul_f32_e32 v17, v17, v9
	v_add_f32_e32 v136, 1.0, v136
	v_add_f32_e32 v137, 1.0, v137
	v_rcp_f32_e32 v136, v136
	v_rcp_f32_e32 v137, v137
	s_nop 0
	v_mul_f32_e32 v13, v13, v136
	v_mul_f32_e32 v17, v17, v137
	v_cvt_pk_bf16_f32 v13, v13, v17
	ds_write_b16 v188, v13 offset:432
	ds_write_b16_d16_hi v188, v13 offset:464
	v_mul_f32_e32 v18, v18, v244
	v_mul_f32_e32 v22, v22, v244
	v_mul_f32_e32 v26, v26, v244
	v_mul_f32_e32 v30, v30, v244
	v_mul_f32_e32 v136, 0xbfb8aa3b, v18
	v_mul_f32_e32 v137, 0xbfb8aa3b, v22
	v_exp_f32_e32 v136, v136
	v_exp_f32_e32 v137, v137
	v_mul_f32_e32 v26, v26, v18
	v_mul_f32_e32 v30, v30, v22
	v_add_f32_e32 v136, 1.0, v136
	v_add_f32_e32 v137, 1.0, v137
	v_rcp_f32_e32 v136, v136
	v_rcp_f32_e32 v137, v137
	s_nop 0
	v_mul_f32_e32 v26, v26, v136
	v_mul_f32_e32 v30, v30, v137
	v_cvt_pk_bf16_f32 v26, v26, v30
	ds_write_b16 v188, v26 offset:2304
	ds_write_b16_d16_hi v188, v26 offset:2336
	v_mul_f32_e32 v19, v19, v245
	v_mul_f32_e32 v23, v23, v245
	v_mul_f32_e32 v27, v27, v245
	v_mul_f32_e32 v31, v31, v245
	v_mul_f32_e32 v136, 0xbfb8aa3b, v19
	v_mul_f32_e32 v137, 0xbfb8aa3b, v23
	v_exp_f32_e32 v136, v136
	v_exp_f32_e32 v137, v137
	v_mul_f32_e32 v27, v27, v19
	v_mul_f32_e32 v31, v31, v23
	v_add_f32_e32 v136, 1.0, v136
	v_add_f32_e32 v137, 1.0, v137
	v_rcp_f32_e32 v136, v136
	v_rcp_f32_e32 v137, v137
	s_nop 0
	v_mul_f32_e32 v27, v27, v136
	v_mul_f32_e32 v31, v31, v137
	v_cvt_pk_bf16_f32 v27, v27, v31
	ds_write_b16 v188, v27 offset:2448
	ds_write_b16_d16_hi v188, v27 offset:2480
	v_mul_f32_e32 v20, v20, v246
	v_mul_f32_e32 v24, v24, v246
	v_mul_f32_e32 v28, v28, v246
	v_mul_f32_e32 v32, v32, v246
	v_mul_f32_e32 v136, 0xbfb8aa3b, v20
	v_mul_f32_e32 v137, 0xbfb8aa3b, v24
	v_exp_f32_e32 v136, v136
	v_exp_f32_e32 v137, v137
	v_mul_f32_e32 v28, v28, v20
	v_mul_f32_e32 v32, v32, v24
	v_add_f32_e32 v136, 1.0, v136
	v_add_f32_e32 v137, 1.0, v137
	v_rcp_f32_e32 v136, v136
	v_rcp_f32_e32 v137, v137
	s_nop 0
	v_mul_f32_e32 v28, v28, v136
	v_mul_f32_e32 v32, v32, v137
	v_cvt_pk_bf16_f32 v28, v28, v32
	ds_write_b16 v188, v28 offset:2592
	ds_write_b16_d16_hi v188, v28 offset:2624
	v_mul_f32_e32 v21, v21, v247
	v_mul_f32_e32 v25, v25, v247
	v_mul_f32_e32 v29, v29, v247
	v_mul_f32_e32 v33, v33, v247
	v_mul_f32_e32 v136, 0xbfb8aa3b, v21
	v_mul_f32_e32 v137, 0xbfb8aa3b, v25
	v_exp_f32_e32 v136, v136
	v_exp_f32_e32 v137, v137
	v_mul_f32_e32 v29, v29, v21
	v_mul_f32_e32 v33, v33, v25
	v_add_f32_e32 v136, 1.0, v136
	v_add_f32_e32 v137, 1.0, v137
	v_rcp_f32_e32 v136, v136
	v_rcp_f32_e32 v137, v137
	s_nop 0
	v_mul_f32_e32 v29, v29, v136
	v_mul_f32_e32 v33, v33, v137
	v_cvt_pk_bf16_f32 v29, v29, v33
	ds_write_b16 v188, v29 offset:2736
	ds_write_b16_d16_hi v188, v29 offset:2768
	v_mul_f32_e32 v34, v34, v248
	v_mul_f32_e32 v38, v38, v248
	v_mul_f32_e32 v42, v42, v248
	v_mul_f32_e32 v46, v46, v248
	v_mul_f32_e32 v136, 0xbfb8aa3b, v34
	v_mul_f32_e32 v137, 0xbfb8aa3b, v38
	v_exp_f32_e32 v136, v136
	v_exp_f32_e32 v137, v137
	v_mul_f32_e32 v42, v42, v34
	v_mul_f32_e32 v46, v46, v38
	v_add_f32_e32 v136, 1.0, v136
	v_add_f32_e32 v137, 1.0, v137
	v_rcp_f32_e32 v136, v136
	v_rcp_f32_e32 v137, v137
	s_nop 0
	v_mul_f32_e32 v42, v42, v136
	v_mul_f32_e32 v46, v46, v137
	v_cvt_pk_bf16_f32 v42, v42, v46
	ds_write_b16 v188, v42 offset:4608
	ds_write_b16_d16_hi v188, v42 offset:4640
	v_mul_f32_e32 v35, v35, v249
	v_mul_f32_e32 v39, v39, v249
	v_mul_f32_e32 v43, v43, v249
	v_mul_f32_e32 v47, v47, v249
	v_mul_f32_e32 v136, 0xbfb8aa3b, v35
	v_mul_f32_e32 v137, 0xbfb8aa3b, v39
	v_exp_f32_e32 v136, v136
	v_exp_f32_e32 v137, v137
	v_mul_f32_e32 v43, v43, v35
	v_mul_f32_e32 v47, v47, v39
	v_add_f32_e32 v136, 1.0, v136
	v_add_f32_e32 v137, 1.0, v137
	v_rcp_f32_e32 v136, v136
	v_rcp_f32_e32 v137, v137
	s_nop 0
	v_mul_f32_e32 v43, v43, v136
	v_mul_f32_e32 v47, v47, v137
	v_cvt_pk_bf16_f32 v43, v43, v47
	ds_write_b16 v188, v43 offset:4752
	ds_write_b16_d16_hi v188, v43 offset:4784
	v_mul_f32_e32 v36, v36, v250
	v_mul_f32_e32 v40, v40, v250
	v_mul_f32_e32 v44, v44, v250
	v_mul_f32_e32 v48, v48, v250
	v_mul_f32_e32 v136, 0xbfb8aa3b, v36
	v_mul_f32_e32 v137, 0xbfb8aa3b, v40
	v_exp_f32_e32 v136, v136
	v_exp_f32_e32 v137, v137
	v_mul_f32_e32 v44, v44, v36
	v_mul_f32_e32 v48, v48, v40
	v_add_f32_e32 v136, 1.0, v136
	v_add_f32_e32 v137, 1.0, v137
	v_rcp_f32_e32 v136, v136
	v_rcp_f32_e32 v137, v137
	s_nop 0
	v_mul_f32_e32 v44, v44, v136
	v_mul_f32_e32 v48, v48, v137
	v_cvt_pk_bf16_f32 v44, v44, v48
	ds_write_b16 v188, v44 offset:4896
	ds_write_b16_d16_hi v188, v44 offset:4928
	v_mul_f32_e32 v37, v37, v251
	v_mul_f32_e32 v41, v41, v251
	v_mul_f32_e32 v45, v45, v251
	v_mul_f32_e32 v49, v49, v251
	v_mul_f32_e32 v136, 0xbfb8aa3b, v37
	v_mul_f32_e32 v137, 0xbfb8aa3b, v41
	v_exp_f32_e32 v136, v136
	v_exp_f32_e32 v137, v137
	v_mul_f32_e32 v45, v45, v37
	v_mul_f32_e32 v49, v49, v41
	v_add_f32_e32 v136, 1.0, v136
	v_add_f32_e32 v137, 1.0, v137
	v_rcp_f32_e32 v136, v136
	v_rcp_f32_e32 v137, v137
	s_nop 0
	v_mul_f32_e32 v45, v45, v136
	v_mul_f32_e32 v49, v49, v137
	v_cvt_pk_bf16_f32 v45, v45, v49
	ds_write_b16 v188, v45 offset:5040
	ds_write_b16_d16_hi v188, v45 offset:5072
	v_mul_f32_e32 v50, v50, v252
	v_mul_f32_e32 v54, v54, v252
	v_mul_f32_e32 v58, v58, v252
	v_mul_f32_e32 v62, v62, v252
	v_mul_f32_e32 v136, 0xbfb8aa3b, v50
	v_mul_f32_e32 v137, 0xbfb8aa3b, v54
	v_exp_f32_e32 v136, v136
	v_exp_f32_e32 v137, v137
	v_mul_f32_e32 v58, v58, v50
	v_mul_f32_e32 v62, v62, v54
	v_add_f32_e32 v136, 1.0, v136
	v_add_f32_e32 v137, 1.0, v137
	v_rcp_f32_e32 v136, v136
	v_rcp_f32_e32 v137, v137
	s_nop 0
	v_mul_f32_e32 v58, v58, v136
	v_mul_f32_e32 v62, v62, v137
	v_cvt_pk_bf16_f32 v58, v58, v62
	ds_write_b16 v188, v58 offset:6912
	ds_write_b16_d16_hi v188, v58 offset:6944
	v_mul_f32_e32 v51, v51, v253
	v_mul_f32_e32 v55, v55, v253
	v_mul_f32_e32 v59, v59, v253
	v_mul_f32_e32 v63, v63, v253
	v_mul_f32_e32 v136, 0xbfb8aa3b, v51
	v_mul_f32_e32 v137, 0xbfb8aa3b, v55
	v_exp_f32_e32 v136, v136
	v_exp_f32_e32 v137, v137
	v_mul_f32_e32 v59, v59, v51
	v_mul_f32_e32 v63, v63, v55
	v_add_f32_e32 v136, 1.0, v136
	v_add_f32_e32 v137, 1.0, v137
	v_rcp_f32_e32 v136, v136
	v_rcp_f32_e32 v137, v137
	s_nop 0
	v_mul_f32_e32 v59, v59, v136
	v_mul_f32_e32 v63, v63, v137
	v_cvt_pk_bf16_f32 v59, v59, v63
	ds_write_b16 v188, v59 offset:7056
	ds_write_b16_d16_hi v188, v59 offset:7088
	v_mul_f32_e32 v52, v52, v254
	v_mul_f32_e32 v56, v56, v254
	v_mul_f32_e32 v60, v60, v254
	v_mul_f32_e32 v64, v64, v254
	v_mul_f32_e32 v136, 0xbfb8aa3b, v52
	v_mul_f32_e32 v137, 0xbfb8aa3b, v56
	v_exp_f32_e32 v136, v136
	v_exp_f32_e32 v137, v137
	v_mul_f32_e32 v60, v60, v52
	v_mul_f32_e32 v64, v64, v56
	v_add_f32_e32 v136, 1.0, v136
	v_add_f32_e32 v137, 1.0, v137
	v_rcp_f32_e32 v136, v136
	v_rcp_f32_e32 v137, v137
	s_nop 0
	v_mul_f32_e32 v60, v60, v136
	v_mul_f32_e32 v64, v64, v137
	v_cvt_pk_bf16_f32 v60, v60, v64
	ds_write_b16 v188, v60 offset:7200
	ds_write_b16_d16_hi v188, v60 offset:7232
	v_mul_f32_e32 v53, v53, v255
	v_mul_f32_e32 v57, v57, v255
	v_mul_f32_e32 v61, v61, v255
	v_mul_f32_e32 v65, v65, v255
	v_mul_f32_e32 v136, 0xbfb8aa3b, v53
	v_mul_f32_e32 v137, 0xbfb8aa3b, v57
	v_exp_f32_e32 v136, v136
	v_exp_f32_e32 v137, v137
	v_mul_f32_e32 v61, v61, v53
	v_mul_f32_e32 v65, v65, v57
	v_add_f32_e32 v136, 1.0, v136
	v_add_f32_e32 v137, 1.0, v137
	v_rcp_f32_e32 v136, v136
	v_rcp_f32_e32 v137, v137
	s_nop 0
	v_mul_f32_e32 v61, v61, v136
	v_mul_f32_e32 v65, v65, v137
	v_cvt_pk_bf16_f32 v61, v61, v65
	ds_write_b16 v188, v61 offset:7344
	ds_write_b16_d16_hi v188, v61 offset:7376
	s_waitcnt lgkmcnt(0)
	s_barrier
	ds_read_b128 v[144:147], v189
	ds_read_b128 v[148:151], v189 offset:4608
	ds_read_b128 v[172:175], v189 offset:9216
	ds_read_b128 v[176:179], v189 offset:13824
	s_mov_b32 s56, s58
	s_mov_b32 s57, s59
	s_waitcnt lgkmcnt(3)
	global_store_dwordx4 v243, v[144:147], s[56:57]
	s_add_u32 s56, s56, 0x59000
	s_addc_u32 s57, s57, 0
	s_waitcnt lgkmcnt(2)
	global_store_dwordx4 v243, v[148:151], s[56:57]
	s_add_u32 s56, s56, 0x59000
	s_addc_u32 s57, s57, 0
	s_waitcnt lgkmcnt(1)
	global_store_dwordx4 v243, v[172:175], s[56:57]
	s_add_u32 s56, s56, 0x59000
	s_addc_u32 s57, s57, 0
	s_waitcnt lgkmcnt(0)
	global_store_dwordx4 v243, v[176:179], s[56:57]
	s_add_u32 s58, s58, 0x400
	s_addc_u32 s59, s59, 0
	s_barrier
	v_mul_f32_e32 v66, v66, v152
	v_mul_f32_e32 v70, v70, v152
	v_mul_f32_e32 v74, v74, v152
	v_mul_f32_e32 v78, v78, v152
	v_mul_f32_e32 v136, 0xbfb8aa3b, v66
	v_mul_f32_e32 v137, 0xbfb8aa3b, v70
	v_exp_f32_e32 v136, v136
	v_exp_f32_e32 v137, v137
	v_mul_f32_e32 v74, v74, v66
	v_mul_f32_e32 v78, v78, v70
	v_add_f32_e32 v136, 1.0, v136
	v_add_f32_e32 v137, 1.0, v137
	v_rcp_f32_e32 v136, v136
	v_rcp_f32_e32 v137, v137
	s_nop 0
	v_mul_f32_e32 v74, v74, v136
	v_mul_f32_e32 v78, v78, v137
	v_cvt_pk_bf16_f32 v74, v74, v78
	ds_write_b16 v188, v74
	ds_write_b16_d16_hi v188, v74 offset:32
	v_mul_f32_e32 v67, v67, v153
	v_mul_f32_e32 v71, v71, v153
	v_mul_f32_e32 v75, v75, v153
	v_mul_f32_e32 v79, v79, v153
	v_mul_f32_e32 v136, 0xbfb8aa3b, v67
	v_mul_f32_e32 v137, 0xbfb8aa3b, v71
	v_exp_f32_e32 v136, v136
	v_exp_f32_e32 v137, v137
	v_mul_f32_e32 v75, v75, v67
	v_mul_f32_e32 v79, v79, v71
	v_add_f32_e32 v136, 1.0, v136
	v_add_f32_e32 v137, 1.0, v137
	v_rcp_f32_e32 v136, v136
	v_rcp_f32_e32 v137, v137
	s_nop 0
	v_mul_f32_e32 v75, v75, v136
	v_mul_f32_e32 v79, v79, v137
	v_cvt_pk_bf16_f32 v75, v75, v79
	ds_write_b16 v188, v75 offset:144
	ds_write_b16_d16_hi v188, v75 offset:176
	v_mul_f32_e32 v68, v68, v154
	v_mul_f32_e32 v72, v72, v154
	v_mul_f32_e32 v76, v76, v154
	v_mul_f32_e32 v80, v80, v154
	v_mul_f32_e32 v136, 0xbfb8aa3b, v68
	v_mul_f32_e32 v137, 0xbfb8aa3b, v72
	v_exp_f32_e32 v136, v136
	v_exp_f32_e32 v137, v137
	v_mul_f32_e32 v76, v76, v68
	v_mul_f32_e32 v80, v80, v72
	v_add_f32_e32 v136, 1.0, v136
	v_add_f32_e32 v137, 1.0, v137
	v_rcp_f32_e32 v136, v136
	v_rcp_f32_e32 v137, v137
	s_nop 0
	v_mul_f32_e32 v76, v76, v136
	v_mul_f32_e32 v80, v80, v137
	v_cvt_pk_bf16_f32 v76, v76, v80
	ds_write_b16 v188, v76 offset:288
	ds_write_b16_d16_hi v188, v76 offset:320
	v_mul_f32_e32 v69, v69, v155
	v_mul_f32_e32 v73, v73, v155
	v_mul_f32_e32 v77, v77, v155
	v_mul_f32_e32 v81, v81, v155
	v_mul_f32_e32 v136, 0xbfb8aa3b, v69
	v_mul_f32_e32 v137, 0xbfb8aa3b, v73
	v_exp_f32_e32 v136, v136
	v_exp_f32_e32 v137, v137
	v_mul_f32_e32 v77, v77, v69
	v_mul_f32_e32 v81, v81, v73
	v_add_f32_e32 v136, 1.0, v136
	v_add_f32_e32 v137, 1.0, v137
	v_rcp_f32_e32 v136, v136
	v_rcp_f32_e32 v137, v137
	s_nop 0
	v_mul_f32_e32 v77, v77, v136
	v_mul_f32_e32 v81, v81, v137
	v_cvt_pk_bf16_f32 v77, v77, v81
	ds_write_b16 v188, v77 offset:432
	ds_write_b16_d16_hi v188, v77 offset:464
	v_mul_f32_e32 v82, v82, v244
	v_mul_f32_e32 v86, v86, v244
	v_mul_f32_e32 v90, v90, v244
	v_mul_f32_e32 v94, v94, v244
	v_mul_f32_e32 v136, 0xbfb8aa3b, v82
	v_mul_f32_e32 v137, 0xbfb8aa3b, v86
	v_exp_f32_e32 v136, v136
	v_exp_f32_e32 v137, v137
	v_mul_f32_e32 v90, v90, v82
	v_mul_f32_e32 v94, v94, v86
	v_add_f32_e32 v136, 1.0, v136
	v_add_f32_e32 v137, 1.0, v137
	v_rcp_f32_e32 v136, v136
	v_rcp_f32_e32 v137, v137
	s_nop 0
	v_mul_f32_e32 v90, v90, v136
	v_mul_f32_e32 v94, v94, v137
	v_cvt_pk_bf16_f32 v90, v90, v94
	ds_write_b16 v188, v90 offset:2304
	ds_write_b16_d16_hi v188, v90 offset:2336
	v_mul_f32_e32 v83, v83, v245
	v_mul_f32_e32 v87, v87, v245
	v_mul_f32_e32 v91, v91, v245
	v_mul_f32_e32 v95, v95, v245
	v_mul_f32_e32 v136, 0xbfb8aa3b, v83
	v_mul_f32_e32 v137, 0xbfb8aa3b, v87
	v_exp_f32_e32 v136, v136
	v_exp_f32_e32 v137, v137
	v_mul_f32_e32 v91, v91, v83
	v_mul_f32_e32 v95, v95, v87
	v_add_f32_e32 v136, 1.0, v136
	v_add_f32_e32 v137, 1.0, v137
	v_rcp_f32_e32 v136, v136
	v_rcp_f32_e32 v137, v137
	s_nop 0
	v_mul_f32_e32 v91, v91, v136
	v_mul_f32_e32 v95, v95, v137
	v_cvt_pk_bf16_f32 v91, v91, v95
	ds_write_b16 v188, v91 offset:2448
	ds_write_b16_d16_hi v188, v91 offset:2480
	v_mul_f32_e32 v84, v84, v246
	v_mul_f32_e32 v88, v88, v246
	v_mul_f32_e32 v92, v92, v246
	v_mul_f32_e32 v96, v96, v246
	v_mul_f32_e32 v136, 0xbfb8aa3b, v84
	v_mul_f32_e32 v137, 0xbfb8aa3b, v88
	v_exp_f32_e32 v136, v136
	v_exp_f32_e32 v137, v137
	v_mul_f32_e32 v92, v92, v84
	v_mul_f32_e32 v96, v96, v88
	v_add_f32_e32 v136, 1.0, v136
	v_add_f32_e32 v137, 1.0, v137
	v_rcp_f32_e32 v136, v136
	v_rcp_f32_e32 v137, v137
	s_nop 0
	v_mul_f32_e32 v92, v92, v136
	v_mul_f32_e32 v96, v96, v137
	v_cvt_pk_bf16_f32 v92, v92, v96
	ds_write_b16 v188, v92 offset:2592
	ds_write_b16_d16_hi v188, v92 offset:2624
	v_mul_f32_e32 v85, v85, v247
	v_mul_f32_e32 v89, v89, v247
	v_mul_f32_e32 v93, v93, v247
	v_mul_f32_e32 v97, v97, v247
	v_mul_f32_e32 v136, 0xbfb8aa3b, v85
	v_mul_f32_e32 v137, 0xbfb8aa3b, v89
	v_exp_f32_e32 v136, v136
	v_exp_f32_e32 v137, v137
	v_mul_f32_e32 v93, v93, v85
	v_mul_f32_e32 v97, v97, v89
	v_add_f32_e32 v136, 1.0, v136
	v_add_f32_e32 v137, 1.0, v137
	v_rcp_f32_e32 v136, v136
	v_rcp_f32_e32 v137, v137
	s_nop 0
	v_mul_f32_e32 v93, v93, v136
	v_mul_f32_e32 v97, v97, v137
	v_cvt_pk_bf16_f32 v93, v93, v97
	ds_write_b16 v188, v93 offset:2736
	ds_write_b16_d16_hi v188, v93 offset:2768
	v_mul_f32_e32 v98, v98, v248
	v_mul_f32_e32 v102, v102, v248
	v_mul_f32_e32 v106, v106, v248
	v_mul_f32_e32 v110, v110, v248
	v_mul_f32_e32 v136, 0xbfb8aa3b, v98
	v_mul_f32_e32 v137, 0xbfb8aa3b, v102
	v_exp_f32_e32 v136, v136
	v_exp_f32_e32 v137, v137
	v_mul_f32_e32 v106, v106, v98
	v_mul_f32_e32 v110, v110, v102
	v_add_f32_e32 v136, 1.0, v136
	v_add_f32_e32 v137, 1.0, v137
	v_rcp_f32_e32 v136, v136
	v_rcp_f32_e32 v137, v137
	s_nop 0
	v_mul_f32_e32 v106, v106, v136
	v_mul_f32_e32 v110, v110, v137
	v_cvt_pk_bf16_f32 v106, v106, v110
	ds_write_b16 v188, v106 offset:4608
	ds_write_b16_d16_hi v188, v106 offset:4640
	v_mul_f32_e32 v99, v99, v249
	v_mul_f32_e32 v103, v103, v249
	v_mul_f32_e32 v107, v107, v249
	v_mul_f32_e32 v111, v111, v249
	v_mul_f32_e32 v136, 0xbfb8aa3b, v99
	v_mul_f32_e32 v137, 0xbfb8aa3b, v103
	v_exp_f32_e32 v136, v136
	v_exp_f32_e32 v137, v137
	v_mul_f32_e32 v107, v107, v99
	v_mul_f32_e32 v111, v111, v103
	v_add_f32_e32 v136, 1.0, v136
	v_add_f32_e32 v137, 1.0, v137
	v_rcp_f32_e32 v136, v136
	v_rcp_f32_e32 v137, v137
	s_nop 0
	v_mul_f32_e32 v107, v107, v136
	v_mul_f32_e32 v111, v111, v137
	v_cvt_pk_bf16_f32 v107, v107, v111
	ds_write_b16 v188, v107 offset:4752
	ds_write_b16_d16_hi v188, v107 offset:4784
	v_mul_f32_e32 v100, v100, v250
	v_mul_f32_e32 v104, v104, v250
	v_mul_f32_e32 v108, v108, v250
	v_mul_f32_e32 v112, v112, v250
	v_mul_f32_e32 v136, 0xbfb8aa3b, v100
	v_mul_f32_e32 v137, 0xbfb8aa3b, v104
	v_exp_f32_e32 v136, v136
	v_exp_f32_e32 v137, v137
	v_mul_f32_e32 v108, v108, v100
	v_mul_f32_e32 v112, v112, v104
	v_add_f32_e32 v136, 1.0, v136
	v_add_f32_e32 v137, 1.0, v137
	v_rcp_f32_e32 v136, v136
	v_rcp_f32_e32 v137, v137
	s_nop 0
	v_mul_f32_e32 v108, v108, v136
	v_mul_f32_e32 v112, v112, v137
	v_cvt_pk_bf16_f32 v108, v108, v112
	ds_write_b16 v188, v108 offset:4896
	ds_write_b16_d16_hi v188, v108 offset:4928
	v_mul_f32_e32 v101, v101, v251
	v_mul_f32_e32 v105, v105, v251
	v_mul_f32_e32 v109, v109, v251
	v_mul_f32_e32 v113, v113, v251
	v_mul_f32_e32 v136, 0xbfb8aa3b, v101
	v_mul_f32_e32 v137, 0xbfb8aa3b, v105
	v_exp_f32_e32 v136, v136
	v_exp_f32_e32 v137, v137
	v_mul_f32_e32 v109, v109, v101
	v_mul_f32_e32 v113, v113, v105
	v_add_f32_e32 v136, 1.0, v136
	v_add_f32_e32 v137, 1.0, v137
	v_rcp_f32_e32 v136, v136
	v_rcp_f32_e32 v137, v137
	s_nop 0
	v_mul_f32_e32 v109, v109, v136
	v_mul_f32_e32 v113, v113, v137
	v_cvt_pk_bf16_f32 v109, v109, v113
	ds_write_b16 v188, v109 offset:5040
	ds_write_b16_d16_hi v188, v109 offset:5072
	v_mul_f32_e32 v114, v114, v252
	v_mul_f32_e32 v118, v118, v252
	v_mul_f32_e32 v122, v122, v252
	v_mul_f32_e32 v126, v126, v252
	v_mul_f32_e32 v136, 0xbfb8aa3b, v114
	v_mul_f32_e32 v137, 0xbfb8aa3b, v118
	v_exp_f32_e32 v136, v136
	v_exp_f32_e32 v137, v137
	v_mul_f32_e32 v122, v122, v114
	v_mul_f32_e32 v126, v126, v118
	v_add_f32_e32 v136, 1.0, v136
	v_add_f32_e32 v137, 1.0, v137
	v_rcp_f32_e32 v136, v136
	v_rcp_f32_e32 v137, v137
	s_nop 0
	v_mul_f32_e32 v122, v122, v136
	v_mul_f32_e32 v126, v126, v137
	v_cvt_pk_bf16_f32 v122, v122, v126
	ds_write_b16 v188, v122 offset:6912
	ds_write_b16_d16_hi v188, v122 offset:6944
	v_mul_f32_e32 v115, v115, v253
	v_mul_f32_e32 v119, v119, v253
	v_mul_f32_e32 v123, v123, v253
	v_mul_f32_e32 v127, v127, v253
	v_mul_f32_e32 v136, 0xbfb8aa3b, v115
	v_mul_f32_e32 v137, 0xbfb8aa3b, v119
	v_exp_f32_e32 v136, v136
	v_exp_f32_e32 v137, v137
	v_mul_f32_e32 v123, v123, v115
	v_mul_f32_e32 v127, v127, v119
	v_add_f32_e32 v136, 1.0, v136
	v_add_f32_e32 v137, 1.0, v137
	v_rcp_f32_e32 v136, v136
	v_rcp_f32_e32 v137, v137
	s_nop 0
	v_mul_f32_e32 v123, v123, v136
	v_mul_f32_e32 v127, v127, v137
	v_cvt_pk_bf16_f32 v123, v123, v127
	ds_write_b16 v188, v123 offset:7056
	ds_write_b16_d16_hi v188, v123 offset:7088
	v_mul_f32_e32 v116, v116, v254
	v_mul_f32_e32 v120, v120, v254
	v_mul_f32_e32 v124, v124, v254
	v_mul_f32_e32 v128, v128, v254
	v_mul_f32_e32 v136, 0xbfb8aa3b, v116
	v_mul_f32_e32 v137, 0xbfb8aa3b, v120
	v_exp_f32_e32 v136, v136
	v_exp_f32_e32 v137, v137
	v_mul_f32_e32 v124, v124, v116
	v_mul_f32_e32 v128, v128, v120
	v_add_f32_e32 v136, 1.0, v136
	v_add_f32_e32 v137, 1.0, v137
	v_rcp_f32_e32 v136, v136
	v_rcp_f32_e32 v137, v137
	s_nop 0
	v_mul_f32_e32 v124, v124, v136
	v_mul_f32_e32 v128, v128, v137
	v_cvt_pk_bf16_f32 v124, v124, v128
	ds_write_b16 v188, v124 offset:7200
	ds_write_b16_d16_hi v188, v124 offset:7232
	v_mul_f32_e32 v117, v117, v255
	v_mul_f32_e32 v121, v121, v255
	v_mul_f32_e32 v125, v125, v255
	v_mul_f32_e32 v129, v129, v255
	v_mul_f32_e32 v136, 0xbfb8aa3b, v117
	v_mul_f32_e32 v137, 0xbfb8aa3b, v121
	v_exp_f32_e32 v136, v136
	v_exp_f32_e32 v137, v137
	v_mul_f32_e32 v125, v125, v117
	v_mul_f32_e32 v129, v129, v121
	v_add_f32_e32 v136, 1.0, v136
	v_add_f32_e32 v137, 1.0, v137
	v_rcp_f32_e32 v136, v136
	v_rcp_f32_e32 v137, v137
	s_nop 0
	v_mul_f32_e32 v125, v125, v136
	v_mul_f32_e32 v129, v129, v137
	v_cvt_pk_bf16_f32 v125, v125, v129
	ds_write_b16 v188, v125 offset:7344
	ds_write_b16_d16_hi v188, v125 offset:7376
	s_waitcnt lgkmcnt(0)
	s_barrier
	ds_read_b128 v[144:147], v189
	ds_read_b128 v[148:151], v189 offset:4608
	ds_read_b128 v[172:175], v189 offset:9216
	ds_read_b128 v[176:179], v189 offset:13824
	s_mov_b32 s56, s58
	s_mov_b32 s57, s59
	s_waitcnt lgkmcnt(3)
	global_store_dwordx4 v243, v[144:147], s[56:57]
	s_add_u32 s56, s56, 0x59000
	s_addc_u32 s57, s57, 0
	s_waitcnt lgkmcnt(2)
	global_store_dwordx4 v243, v[148:151], s[56:57]
	s_add_u32 s56, s56, 0x59000
	s_addc_u32 s57, s57, 0
	s_waitcnt lgkmcnt(1)
	global_store_dwordx4 v243, v[172:175], s[56:57]
	s_add_u32 s56, s56, 0x59000
	s_addc_u32 s57, s57, 0
	s_waitcnt lgkmcnt(0)
	global_store_dwordx4 v243, v[176:179], s[56:57]
	s_cmp_lt_u32 s55, 5
	s_barrier
	s_cbranch_scc0 .Lgu2_lastp
	v_mov_b32_e32 v2, 0
	v_mov_b32_e32 v3, 0
	v_mov_b32_e32 v4, 0
	v_mov_b32_e32 v5, 0
	v_mov_b32_e32 v6, 0
	v_mov_b32_e32 v7, 0
	v_mov_b32_e32 v8, 0
	v_mov_b32_e32 v9, 0
	v_mov_b32_e32 v10, 0
	v_mov_b32_e32 v11, 0
	v_mov_b32_e32 v12, 0
	v_mov_b32_e32 v13, 0
	v_mov_b32_e32 v14, 0
	v_mov_b32_e32 v15, 0
	v_mov_b32_e32 v16, 0
	v_mov_b32_e32 v17, 0
	v_mov_b32_e32 v18, 0
	v_mov_b32_e32 v19, 0
	v_mov_b32_e32 v20, 0
	v_mov_b32_e32 v21, 0
	v_mov_b32_e32 v22, 0
	v_mov_b32_e32 v23, 0
	v_mov_b32_e32 v24, 0
	v_mov_b32_e32 v25, 0
	v_mov_b32_e32 v26, 0
	v_mov_b32_e32 v27, 0
	v_mov_b32_e32 v28, 0
	v_mov_b32_e32 v29, 0
	v_mov_b32_e32 v30, 0
	v_mov_b32_e32 v31, 0
	v_mov_b32_e32 v32, 0
	v_mov_b32_e32 v33, 0
	v_mov_b32_e32 v34, 0
	v_mov_b32_e32 v35, 0
	v_mov_b32_e32 v36, 0
	v_mov_b32_e32 v37, 0
	v_mov_b32_e32 v38, 0
	v_mov_b32_e32 v39, 0
	v_mov_b32_e32 v40, 0
	v_mov_b32_e32 v41, 0
	v_mov_b32_e32 v42, 0
	v_mov_b32_e32 v43, 0
	v_mov_b32_e32 v44, 0
	v_mov_b32_e32 v45, 0
	v_mov_b32_e32 v46, 0
	v_mov_b32_e32 v47, 0
	v_mov_b32_e32 v48, 0
	v_mov_b32_e32 v49, 0
	v_mov_b32_e32 v50, 0
	v_mov_b32_e32 v51, 0
	v_mov_b32_e32 v52, 0
	v_mov_b32_e32 v53, 0
	v_mov_b32_e32 v54, 0
	v_mov_b32_e32 v55, 0
	v_mov_b32_e32 v56, 0
	v_mov_b32_e32 v57, 0
	v_mov_b32_e32 v58, 0
	v_mov_b32_e32 v59, 0
	v_mov_b32_e32 v60, 0
	v_mov_b32_e32 v61, 0
	v_mov_b32_e32 v62, 0
	v_mov_b32_e32 v63, 0
	v_mov_b32_e32 v64, 0
	v_mov_b32_e32 v65, 0
	v_mov_b32_e32 v66, 0
	v_mov_b32_e32 v67, 0
	v_mov_b32_e32 v68, 0
	v_mov_b32_e32 v69, 0
	v_mov_b32_e32 v70, 0
	v_mov_b32_e32 v71, 0
	v_mov_b32_e32 v72, 0
	v_mov_b32_e32 v73, 0
	v_mov_b32_e32 v74, 0
	v_mov_b32_e32 v75, 0
	v_mov_b32_e32 v76, 0
	v_mov_b32_e32 v77, 0
	v_mov_b32_e32 v78, 0
	v_mov_b32_e32 v79, 0
	v_mov_b32_e32 v80, 0
	v_mov_b32_e32 v81, 0
	v_mov_b32_e32 v82, 0
	v_mov_b32_e32 v83, 0
	v_mov_b32_e32 v84, 0
	v_mov_b32_e32 v85, 0
	v_mov_b32_e32 v86, 0
	v_mov_b32_e32 v87, 0
	v_mov_b32_e32 v88, 0
	v_mov_b32_e32 v89, 0
	v_mov_b32_e32 v90, 0
	v_mov_b32_e32 v91, 0
	v_mov_b32_e32 v92, 0
	v_mov_b32_e32 v93, 0
	v_mov_b32_e32 v94, 0
	v_mov_b32_e32 v95, 0
	v_mov_b32_e32 v96, 0
	v_mov_b32_e32 v97, 0
	v_mov_b32_e32 v98, 0
	v_mov_b32_e32 v99, 0
	v_mov_b32_e32 v100, 0
	v_mov_b32_e32 v101, 0
	v_mov_b32_e32 v102, 0
	v_mov_b32_e32 v103, 0
	v_mov_b32_e32 v104, 0
	v_mov_b32_e32 v105, 0
	v_mov_b32_e32 v106, 0
	v_mov_b32_e32 v107, 0
	v_mov_b32_e32 v108, 0
	v_mov_b32_e32 v109, 0
	v_mov_b32_e32 v110, 0
	v_mov_b32_e32 v111, 0
	v_mov_b32_e32 v112, 0
	v_mov_b32_e32 v113, 0
	v_mov_b32_e32 v114, 0
	v_mov_b32_e32 v115, 0
	v_mov_b32_e32 v116, 0
	v_mov_b32_e32 v117, 0
	v_mov_b32_e32 v118, 0
	v_mov_b32_e32 v119, 0
	v_mov_b32_e32 v120, 0
	v_mov_b32_e32 v121, 0
	v_mov_b32_e32 v122, 0
	v_mov_b32_e32 v123, 0
	v_mov_b32_e32 v124, 0
	v_mov_b32_e32 v125, 0
	v_mov_b32_e32 v126, 0
	v_mov_b32_e32 v127, 0
	v_mov_b32_e32 v128, 0
	v_mov_b32_e32 v129, 0
	s_load_dwordx2 s[56:57], s[12:13], 0x1d0
	v_bfe_u32 v241, v131, 4, 2
	s_lshr_b32 s0, s50, 1
	s_lshl_b32 s0, s0, 6
	s_add_i32 s0, s0, s53
	s_lshl_b32 s0, s0, 2
	v_lshlrev_b32_e32 v241, 4, v241
	s_waitcnt lgkmcnt(0)
	s_add_u32 s56, s56, s0
	s_addc_u32 s57, s57, 0
	global_load_dwordx4 v[152:155], v241, s[56:57]
	global_load_dwordx4 v[244:247], v241, s[56:57] offset:64
	global_load_dwordx4 v[248:251], v241, s[56:57] offset:128
	global_load_dwordx4 v[252:255], v241, s[56:57] offset:192
	s_waitcnt vmcnt(12)
	s_barrier
	s_mov_b32 s52, 0
	s_cmpk_lt_u32 s60, 0x100
	s_cselect_b64 vcc, -1, 0
	v_add_u32_e32 v234, s22, v232
	v_add_u32_e32 v236, s28, v232
	v_add_u32_e32 v235, s22, v233
	v_add_u32_e32 v237, s28, v233
	ds_read_b128 v[136:139], v234
	ds_read_b128 v[140:143], v234 offset:2048
	ds_read_b128 v[144:147], v234 offset:4096
	ds_read_b128 v[148:151], v234 offset:6144
	ds_read_b128 v[188:191], v236
	ds_read_b128 v[196:199], v236 offset:2048
	ds_read_b128 v[200:203], v236 offset:4096
	ds_read_b128 v[204:207], v236 offset:6144
	ds_read_b128 v[172:175], v235
	ds_read_b128 v[176:179], v235 offset:2048
	ds_read_b128 v[180:183], v235 offset:4096
	ds_read_b128 v[184:187], v235 offset:6144
	ds_read_b128 v[212:215], v237
	ds_read_b128 v[216:219], v237 offset:2048
	ds_read_b128 v[220:223], v237 offset:4096
	ds_read_b128 v[224:227], v237 offset:6144
	s_add_i32 m0, s51, 0xc000
	s_nop 0
	global_load_lds_dwordx4 v228, s[44:45]
	s_add_i32 m0, s51, 0xc400
	s_nop 0
	global_load_lds_dwordx4 v230, s[44:45]
	s_add_i32 m0, s51, 0xe000
	s_nop 0
	global_load_lds_dwordx4 v229, s[44:45]
	s_add_i32 m0, s51, 0xe400
	s_nop 0
	global_load_lds_dwordx4 v231, s[44:45]
	s_add_i32 m0, s51, 0x10000
	s_nop 0
	global_load_lds_dwordx4 v228, s[46:47]
	s_add_i32 m0, s51, 0x10400
	s_nop 0
	global_load_lds_dwordx4 v230, s[46:47]
	s_waitcnt lgkmcnt(8)
	s_setprio 1
	s_cbranch_vccz .Lgu2_ap11
	s_setprio 3
.Lgu2_ap11:
	v_mfma_f32_16x16x32_bf16 v[2:5], v[136:139], v[188:191], v[2:5]
	v_mfma_f32_16x16x32_bf16 v[6:9], v[136:139], v[196:199], v[6:9]
	v_mfma_f32_16x16x32_bf16 v[10:13], v[136:139], v[200:203], v[10:13]
	v_mfma_f32_16x16x32_bf16 v[14:17], v[136:139], v[204:207], v[14:17]
	v_mfma_f32_16x16x32_bf16 v[18:21], v[140:143], v[188:191], v[18:21]
	v_mfma_f32_16x16x32_bf16 v[22:25], v[140:143], v[196:199], v[22:25]
	v_mfma_f32_16x16x32_bf16 v[26:29], v[140:143], v[200:203], v[26:29]
	v_mfma_f32_16x16x32_bf16 v[30:33], v[140:143], v[204:207], v[30:33]
	v_mfma_f32_16x16x32_bf16 v[34:37], v[144:147], v[188:191], v[34:37]
	v_mfma_f32_16x16x32_bf16 v[38:41], v[144:147], v[196:199], v[38:41]
	v_mfma_f32_16x16x32_bf16 v[42:45], v[144:147], v[200:203], v[42:45]
	v_mfma_f32_16x16x32_bf16 v[46:49], v[144:147], v[204:207], v[46:49]
	v_mfma_f32_16x16x32_bf16 v[50:53], v[148:151], v[188:191], v[50:53]
	v_mfma_f32_16x16x32_bf16 v[54:57], v[148:151], v[196:199], v[54:57]
	v_mfma_f32_16x16x32_bf16 v[58:61], v[148:151], v[200:203], v[58:61]
	v_mfma_f32_16x16x32_bf16 v[62:65], v[148:151], v[204:207], v[62:65]
	s_waitcnt lgkmcnt(0)
	v_mfma_f32_16x16x32_bf16 v[2:5], v[172:175], v[212:215], v[2:5]
	v_mfma_f32_16x16x32_bf16 v[6:9], v[172:175], v[216:219], v[6:9]
	v_mfma_f32_16x16x32_bf16 v[10:13], v[172:175], v[220:223], v[10:13]
	v_mfma_f32_16x16x32_bf16 v[14:17], v[172:175], v[224:227], v[14:17]
	v_mfma_f32_16x16x32_bf16 v[18:21], v[176:179], v[212:215], v[18:21]
	v_mfma_f32_16x16x32_bf16 v[22:25], v[176:179], v[216:219], v[22:25]
	v_mfma_f32_16x16x32_bf16 v[26:29], v[176:179], v[220:223], v[26:29]
	v_mfma_f32_16x16x32_bf16 v[30:33], v[176:179], v[224:227], v[30:33]
	v_mfma_f32_16x16x32_bf16 v[34:37], v[180:183], v[212:215], v[34:37]
	v_mfma_f32_16x16x32_bf16 v[38:41], v[180:183], v[216:219], v[38:41]
	v_mfma_f32_16x16x32_bf16 v[42:45], v[180:183], v[220:223], v[42:45]
	v_mfma_f32_16x16x32_bf16 v[46:49], v[180:183], v[224:227], v[46:49]
	v_mfma_f32_16x16x32_bf16 v[50:53], v[184:187], v[212:215], v[50:53]
	v_mfma_f32_16x16x32_bf16 v[54:57], v[184:187], v[216:219], v[54:57]
	v_mfma_f32_16x16x32_bf16 v[58:61], v[184:187], v[220:223], v[58:61]
	v_mfma_f32_16x16x32_bf16 v[62:65], v[184:187], v[224:227], v[62:65]
	s_setprio 0
	s_waitcnt vmcnt(18)
	s_barrier
	s_branch .Lgu2_loop_a0
